# P4/P7 residual epilogue: 16 x-loads hoisted, counted vmcnt, batched ssq reduce
# speedup vs baseline: 1.0047x; 1.0047x over previous
; #define PG8_STAGE(bufoff, gbase, voff) do { _Pragma("unroll") for (int _i = 0; _i < 2; ++_i) \
;         __builtin_amdgcn_global_load_lds((const __attribute__((address_space(1))) unsigned*)((const char*)(gbase) + (voff)[_i]), (LAS unsigned*)(lds + (bufoff) + ldsw + _i * 8192), 16, 0, 0); } while (0)
; #define PG8_LDA(dst, b, h) do { _Pragma("unroll") for (int m = 0; m < 4; ++m) _Pragma("unroll") for (int k = 0; k < 2; ++k) dst[m][k] = *(const LAS bf16x8*)(lds + PG8_SA(b, h) + aoff + m * 2048 + k * 1024); } while (0)
; #define PG8_LDB(dst, b, h) do { _Pragma("unroll") for (int n = 0; n < 2; ++n) _Pragma("unroll") for (int k = 0; k < 2; ++k) dst[n][k] = *(const LAS bf16x8*)(lds + PG8_SB(b, h) + boff + n * 2048 + k * 1024); } while (0)
; #define PG8_MMA(ai, bj, At, Bt) do { __builtin_amdgcn_s_setprio(1); _Pragma("unroll") for (int m = 0; m < 4; ++m) _Pragma("unroll") for (int n = 0; n < 2; ++n) _Pragma("unroll") for (int k = 0; k < 2; ++k) \
;         acc[ai][bj][m][n] = __builtin_amdgcn_mfma_f32_16x16x32_bf16(Bt[n][k], At[m][k], acc[ai][bj][m][n], 0, 0, 0); __builtin_amdgcn_s_setprio(0); } while (0)
; #define PG8_WAIT_V(n) asm volatile("s_waitcnt vmcnt(" #n ")" ::: "memory")
; #define PG8_WAIT_L(n) asm volatile("s_waitcnt lgkmcnt(" #n ")" ::: "memory")
; #define PG8_BAR __builtin_amdgcn_s_barrier()
; #define PG8_SCHED __builtin_amdgcn_sched_barrier(0)
; template <class Epi, class SchedT, bool ALIGN_EPI, bool SP2>
; __device__ __forceinline__ void gemm_phase(LAS unsigned char* lds, const int ldk, const int nt, const SchedT& S, const Epi& E) {
;     ...
;         for (int t = 0; t < nt; t += 2) {
;             const bool last = (t == nt - 2);
;             const char* a1 = cA + (size_t)(t + 1) * kstep;
;             const char* a2 = last ? nA : cA + (size_t)(t + 2) * kstep; const char* b2 = last ? nB : cB + (size_t)(t + 2) * kstep;
;             const char* a3 = a2 + kstep; const char* b3 = b2 + kstep;
;             if constexpr (SP2) {
;             PG8_LDB(B0, 0, 0); PG8_LDB(B1, 0, 1); PG8_SCHED; PG8_LDA(At, 0, 0); PG8_STAGE(PG8_SA(1, 1), a1 + hstep, voffA);
;             PG8_WAIT_V(8); PG8_WAIT_L(0); PG8_BAR; PG8_MMA(0, 0, At, B0); PG8_MMA(0, 1, At, B1); PG8_BAR; PG8_SCHED;
;             PG8_LDA(At, 0, 1); PG8_STAGE(PG8_SB(0, 0), b2, voffB); PG8_STAGE(PG8_SB(0, 1), b2 + hstepB, voffB); PG8_STAGE(PG8_SA(0, 0), a2, voffA);
.LBB0_668:
	s_add_u32 s36, s34, 0xfff80080
	s_addc_u32 s37, s35, -1
	s_add_i32 s51, 0, 0x10000
	s_cmp_eq_u32 s22, 28
	s_cselect_b32 s57, s1, s37
	s_cselect_b32 s56, s0, s36
	v_add_u32_e32 v144, s51, v147
	s_cselect_b32 s37, s55, s20
	s_cselect_b32 s36, s54, s13
	s_add_i32 s53, 0, 0x14000
	ds_read_b128 v[140:143], v144
	ds_read_b128 v[150:153], v144 offset:1024
	ds_read_b128 v[154:157], v144 offset:2048
	ds_read_b128 v[158:161], v144 offset:3072
	v_add_u32_e32 v144, s53, v147
	ds_read_b128 v[174:177], v144
	ds_read_b128 v[178:181], v144 offset:1024
	ds_read_b128 v[182:185], v144 offset:2048
	ds_read_b128 v[186:189], v144 offset:3072
	v_lshl_add_u64 v[144:145], s[34:35], 0, v[136:137]
	s_add_i32 m0, s17, 0xc000
	ds_read_b128 v[190:193], v149
	ds_read_b128 v[194:197], v149 offset:1024
	ds_read_b128 v[198:201], v149 offset:2048
	ds_read_b128 v[202:205], v149 offset:3072
	ds_read_b128 v[206:209], v149 offset:4096
	ds_read_b128 v[210:213], v149 offset:5120
	ds_read_b128 v[214:217], v149 offset:6144
	ds_read_b128 v[218:221], v149 offset:7168
	global_load_lds_dwordx4 v[144:145], off
	v_lshl_add_u64 v[144:145], s[34:35], 0, v[138:139]
	s_add_i32 m0, s17, 0xe000
	s_nop 0
	global_load_lds_dwordx4 v[144:145], off
	s_waitcnt vmcnt(8)
	s_waitcnt lgkmcnt(0)
	s_barrier
	s_setprio 1
	s_waitcnt lgkmcnt(0)
	v_mfma_f32_16x16x32_bf16 v[126:129], v[140:143], v[190:193], v[126:129]
	v_mfma_f32_16x16x32_bf16 v[122:125], v[154:157], v[190:193], v[122:125]
	v_mfma_f32_16x16x32_bf16 v[110:113], v[140:143], v[198:201], v[110:113]
	v_mfma_f32_16x16x32_bf16 v[106:109], v[154:157], v[198:201], v[106:109]
	v_mfma_f32_16x16x32_bf16 v[94:97], v[140:143], v[206:209], v[94:97]
	v_mfma_f32_16x16x32_bf16 v[90:93], v[154:157], v[206:209], v[90:93]
	v_mfma_f32_16x16x32_bf16 v[78:81], v[140:143], v[214:217], v[78:81]
	v_mfma_f32_16x16x32_bf16 v[74:77], v[154:157], v[214:217], v[74:77]
	v_mfma_f32_16x16x32_bf16 v[126:129], v[150:153], v[194:197], v[126:129]
	v_mfma_f32_16x16x32_bf16 v[122:125], v[158:161], v[194:197], v[122:125]
	v_mfma_f32_16x16x32_bf16 v[110:113], v[150:153], v[202:205], v[110:113]
	v_mfma_f32_16x16x32_bf16 v[106:109], v[158:161], v[202:205], v[106:109]
	v_mfma_f32_16x16x32_bf16 v[94:97], v[150:153], v[210:213], v[94:97]
	v_mfma_f32_16x16x32_bf16 v[90:93], v[158:161], v[210:213], v[90:93]
	v_mfma_f32_16x16x32_bf16 v[78:81], v[150:153], v[218:221], v[78:81]
	v_mfma_f32_16x16x32_bf16 v[74:77], v[158:161], v[218:221], v[74:77]
	s_setprio 0
	s_setprio 1
	v_mfma_f32_16x16x32_bf16 v[118:121], v[174:177], v[190:193], v[118:121]
	v_mfma_f32_16x16x32_bf16 v[114:117], v[182:185], v[190:193], v[114:117]
	v_mfma_f32_16x16x32_bf16 v[102:105], v[174:177], v[198:201], v[102:105]
	v_mfma_f32_16x16x32_bf16 v[98:101], v[182:185], v[198:201], v[98:101]
	v_mfma_f32_16x16x32_bf16 v[86:89], v[174:177], v[206:209], v[86:89]
	v_mfma_f32_16x16x32_bf16 v[82:85], v[182:185], v[206:209], v[82:85]
	v_mfma_f32_16x16x32_bf16 v[70:73], v[174:177], v[214:217], v[70:73]
	v_mfma_f32_16x16x32_bf16 v[66:69], v[182:185], v[214:217], v[66:69]
	v_mfma_f32_16x16x32_bf16 v[118:121], v[178:181], v[194:197], v[118:121]
	v_mfma_f32_16x16x32_bf16 v[114:117], v[186:189], v[194:197], v[114:117]
	v_mfma_f32_16x16x32_bf16 v[102:105], v[178:181], v[202:205], v[102:105]
	v_mfma_f32_16x16x32_bf16 v[98:101], v[186:189], v[202:205], v[98:101]
	v_mfma_f32_16x16x32_bf16 v[86:89], v[178:181], v[210:213], v[86:89]
	v_mfma_f32_16x16x32_bf16 v[82:85], v[186:189], v[210:213], v[82:85]
	v_mfma_f32_16x16x32_bf16 v[70:73], v[178:181], v[218:221], v[70:73]
	v_mfma_f32_16x16x32_bf16 v[66:69], v[186:189], v[218:221], v[66:69]
	s_setprio 0
	s_barrier
	s_add_i32 s51, s51, s61
	v_lshl_add_u64 v[144:145], s[36:37], 0, v[0:1]
	s_mov_b32 m0, s51
	ds_read_b128 v[190:193], v149 offset:16384
	ds_read_b128 v[194:197], v149 offset:17408
	ds_read_b128 v[198:201], v149 offset:18432
	ds_read_b128 v[202:205], v149 offset:19456
	ds_read_b128 v[206:209], v149 offset:20480
	ds_read_b128 v[210:213], v149 offset:21504
	ds_read_b128 v[214:217], v149 offset:22528
	ds_read_b128 v[218:221], v149 offset:23552
	global_load_lds_dwordx4 v[144:145], off
	s_add_i32 m0, s51, 0x2000
	s_add_u32 s86, s36, 0x20000
	v_lshl_add_u64 v[222:223], s[36:37], 0, v[134:135]
	s_addc_u32 s87, s37, 0
	s_add_i32 s51, s53, s61
	global_load_lds_dwordx4 v[222:223], off
	v_lshl_add_u64 v[224:225], s[86:87], 0, v[0:1]
	s_mov_b32 m0, s51
	v_lshl_add_u64 v[226:227], s[56:57], 0, v[132:133]
	global_load_lds_dwordx4 v[224:225], off
	v_lshl_add_u64 v[224:225], s[86:87], 0, v[134:135]
	s_add_i32 m0, s51, 0x2000
	s_nop 0
	global_load_lds_dwordx4 v[224:225], off
	v_lshl_add_u64 v[224:225], s[56:57], 0, v[130:131]
	s_mov_b32 m0, s17
	s_nop 0
	global_load_lds_dwordx4 v[224:225], off
	s_mov_b32 m0, s62
	s_nop 0
	global_load_lds_dwordx4 v[226:227], off
	s_waitcnt vmcnt(8)
	s_waitcnt lgkmcnt(0)
	s_barrier
; #define PG8_STAGE(bufoff, gbase, voff) do { _Pragma("unroll") for (int _i = 0; _i < 2; ++_i) \
;         __builtin_amdgcn_global_load_lds((const __attribute__((address_space(1))) unsigned*)((const char*)(gbase) + (voff)[_i]), (LAS unsigned*)(lds + (bufoff) + ldsw + _i * 8192), 16, 0, 0); } while (0)
; #define PG8_LDA(dst, b, h) do { _Pragma("unroll") for (int m = 0; m < 4; ++m) _Pragma("unroll") for (int k = 0; k < 2; ++k) dst[m][k] = *(const LAS bf16x8*)(lds + PG8_SA(b, h) + aoff + m * 2048 + k * 1024); } while (0)
; #define PG8_LDB(dst, b, h) do { _Pragma("unroll") for (int n = 0; n < 2; ++n) _Pragma("unroll") for (int k = 0; k < 2; ++k) dst[n][k] = *(const LAS bf16x8*)(lds + PG8_SB(b, h) + boff + n * 2048 + k * 1024); } while (0)
; #define PG8_MMA(ai, bj, At, Bt) do { __builtin_amdgcn_s_setprio(1); _Pragma("unroll") for (int m = 0; m < 4; ++m) _Pragma("unroll") for (int n = 0; n < 2; ++n) _Pragma("unroll") for (int k = 0; k < 2; ++k) \
;         acc[ai][bj][m][n] = __builtin_amdgcn_mfma_f32_16x16x32_bf16(Bt[n][k], At[m][k], acc[ai][bj][m][n], 0, 0, 0); __builtin_amdgcn_s_setprio(0); } while (0)
; #define PG8_WAIT_V(n) asm volatile("s_waitcnt vmcnt(" #n ")" ::: "memory")
; #define PG8_WAIT_L(n) asm volatile("s_waitcnt lgkmcnt(" #n ")" ::: "memory")
; #define PG8_BAR __builtin_amdgcn_s_barrier()
; #define PG8_SCHED __builtin_amdgcn_sched_barrier(0)
; template <class Epi, class SchedT, bool ALIGN_EPI, bool SP2>
; __device__ __forceinline__ void gemm_phase(LAS unsigned char* lds, const int ldk, const int nt, const SchedT& S, const Epi& E) {
;     ...
;             PG8_WAIT_V(8); PG8_WAIT_L(0); PG8_BAR; PG8_MMA(0, 0, At, B0); PG8_MMA(0, 1, At, B1); PG8_BAR; PG8_SCHED;
;             PG8_LDA(At, 0, 1); PG8_STAGE(PG8_SB(0, 0), b2, voffB); PG8_STAGE(PG8_SB(0, 1), b2 + hstepB, voffB); PG8_STAGE(PG8_SA(0, 0), a2, voffA);
;             PG8_WAIT_V(8); PG8_WAIT_L(0); PG8_BAR; PG8_MMA(1, 0, At, B0); PG8_MMA(1, 1, At, B1); PG8_BAR; PG8_SCHED;
;             PG8_LDB(B0, 1, 0); PG8_LDB(B1, 1, 1); PG8_SCHED; PG8_LDA(At, 1, 0); PG8_STAGE(PG8_SA(0, 1), a2 + hstep, voffA);
;             PG8_WAIT_V(8); PG8_WAIT_L(0); PG8_BAR; PG8_MMA(0, 0, At, B0); PG8_MMA(0, 1, At, B1); PG8_BAR; PG8_SCHED;
	s_setprio 1
	s_waitcnt lgkmcnt(0)
	v_mfma_f32_16x16x32_bf16 v[62:65], v[140:143], v[190:193], v[62:65]
	v_mfma_f32_16x16x32_bf16 v[58:61], v[154:157], v[190:193], v[58:61]
	v_mfma_f32_16x16x32_bf16 v[46:49], v[140:143], v[198:201], v[46:49]
	v_mfma_f32_16x16x32_bf16 v[42:45], v[154:157], v[198:201], v[42:45]
	v_mfma_f32_16x16x32_bf16 v[30:33], v[140:143], v[206:209], v[30:33]
	v_mfma_f32_16x16x32_bf16 v[26:29], v[154:157], v[206:209], v[26:29]
	v_mfma_f32_16x16x32_bf16 v[14:17], v[140:143], v[214:217], v[14:17]
	v_mfma_f32_16x16x32_bf16 v[10:13], v[154:157], v[214:217], v[10:13]
	v_mfma_f32_16x16x32_bf16 v[62:65], v[150:153], v[194:197], v[62:65]
	v_mfma_f32_16x16x32_bf16 v[58:61], v[158:161], v[194:197], v[58:61]
	v_mfma_f32_16x16x32_bf16 v[46:49], v[150:153], v[202:205], v[46:49]
	v_mfma_f32_16x16x32_bf16 v[42:45], v[158:161], v[202:205], v[42:45]
	v_mfma_f32_16x16x32_bf16 v[30:33], v[150:153], v[210:213], v[30:33]
	v_mfma_f32_16x16x32_bf16 v[26:29], v[158:161], v[210:213], v[26:29]
	v_mfma_f32_16x16x32_bf16 v[14:17], v[150:153], v[218:221], v[14:17]
	v_mfma_f32_16x16x32_bf16 v[10:13], v[158:161], v[218:221], v[10:13]
	s_setprio 0
	s_setprio 1
	v_mfma_f32_16x16x32_bf16 v[54:57], v[174:177], v[190:193], v[54:57]
	v_mfma_f32_16x16x32_bf16 v[50:53], v[182:185], v[190:193], v[50:53]
	v_mfma_f32_16x16x32_bf16 v[38:41], v[174:177], v[198:201], v[38:41]
	v_mfma_f32_16x16x32_bf16 v[34:37], v[182:185], v[198:201], v[34:37]
	v_mfma_f32_16x16x32_bf16 v[22:25], v[174:177], v[206:209], v[22:25]
	v_mfma_f32_16x16x32_bf16 v[18:21], v[182:185], v[206:209], v[18:21]
	v_mfma_f32_16x16x32_bf16 v[6:9], v[174:177], v[214:217], v[6:9]
	v_mfma_f32_16x16x32_bf16 v[2:5], v[182:185], v[214:217], v[2:5]
	v_mfma_f32_16x16x32_bf16 v[54:57], v[178:181], v[194:197], v[54:57]
	v_mfma_f32_16x16x32_bf16 v[50:53], v[186:189], v[194:197], v[50:53]
	v_mfma_f32_16x16x32_bf16 v[38:41], v[178:181], v[202:205], v[38:41]
	v_mfma_f32_16x16x32_bf16 v[34:37], v[186:189], v[202:205], v[34:37]
	v_mfma_f32_16x16x32_bf16 v[22:25], v[178:181], v[210:213], v[22:25]
	v_mfma_f32_16x16x32_bf16 v[18:21], v[186:189], v[210:213], v[18:21]
	v_mfma_f32_16x16x32_bf16 v[6:9], v[178:181], v[218:221], v[6:9]
	v_mfma_f32_16x16x32_bf16 v[2:5], v[186:189], v[218:221], v[2:5]
	s_setprio 0
	s_barrier
	s_add_i32 s51, 0, 0x18000
	s_add_i32 s53, 0, 0x1c000
	v_add_u32_e32 v158, s51, v147
	v_add_u32_e32 v186, s53, v147
	ds_read_b128 v[140:143], v158
	ds_read_b128 v[150:153], v158 offset:1024
	ds_read_b128 v[154:157], v158 offset:2048
	ds_read_b128 v[158:161], v158 offset:3072
	ds_read_b128 v[174:177], v186
	ds_read_b128 v[178:181], v186 offset:1024
	ds_read_b128 v[182:185], v186 offset:2048
	ds_read_b128 v[186:189], v186 offset:3072
	s_add_u32 s56, s56, 0x80000
	s_addc_u32 s57, s57, 0
	s_mov_b32 m0, s63
	v_lshl_add_u64 v[228:229], s[56:57], 0, v[130:131]
	ds_read_b128 v[190:193], v149 offset:32768
	ds_read_b128 v[194:197], v149 offset:33792
	ds_read_b128 v[198:201], v149 offset:34816
	ds_read_b128 v[202:205], v149 offset:35840
	ds_read_b128 v[206:209], v149 offset:36864
	ds_read_b128 v[210:213], v149 offset:37888
	ds_read_b128 v[214:217], v149 offset:38912
	ds_read_b128 v[218:221], v149 offset:39936
	global_load_lds_dwordx4 v[228:229], off
	v_lshl_add_u64 v[228:229], s[56:57], 0, v[132:133]
	s_mov_b32 m0, s81
	s_nop 0
	global_load_lds_dwordx4 v[228:229], off
	s_waitcnt vmcnt(8)
	s_waitcnt lgkmcnt(0)
	s_barrier
	s_setprio 1
	s_waitcnt lgkmcnt(0)
	v_mfma_f32_16x16x32_bf16 v[126:129], v[140:143], v[190:193], v[126:129]
	v_mfma_f32_16x16x32_bf16 v[122:125], v[154:157], v[190:193], v[122:125]
	v_mfma_f32_16x16x32_bf16 v[110:113], v[140:143], v[198:201], v[110:113]
	v_mfma_f32_16x16x32_bf16 v[106:109], v[154:157], v[198:201], v[106:109]
	v_mfma_f32_16x16x32_bf16 v[94:97], v[140:143], v[206:209], v[94:97]
	v_mfma_f32_16x16x32_bf16 v[90:93], v[154:157], v[206:209], v[90:93]
	v_mfma_f32_16x16x32_bf16 v[78:81], v[140:143], v[214:217], v[78:81]
	v_mfma_f32_16x16x32_bf16 v[74:77], v[154:157], v[214:217], v[74:77]
	v_mfma_f32_16x16x32_bf16 v[126:129], v[150:153], v[194:197], v[126:129]
	v_mfma_f32_16x16x32_bf16 v[122:125], v[158:161], v[194:197], v[122:125]
	v_mfma_f32_16x16x32_bf16 v[110:113], v[150:153], v[202:205], v[110:113]
	v_mfma_f32_16x16x32_bf16 v[106:109], v[158:161], v[202:205], v[106:109]
	v_mfma_f32_16x16x32_bf16 v[94:97], v[150:153], v[210:213], v[94:97]
	v_mfma_f32_16x16x32_bf16 v[90:93], v[158:161], v[210:213], v[90:93]
	v_mfma_f32_16x16x32_bf16 v[78:81], v[150:153], v[218:221], v[78:81]
	v_mfma_f32_16x16x32_bf16 v[74:77], v[158:161], v[218:221], v[74:77]
	s_setprio 0
	s_setprio 1
	v_mfma_f32_16x16x32_bf16 v[118:121], v[174:177], v[190:193], v[118:121]
	v_mfma_f32_16x16x32_bf16 v[114:117], v[182:185], v[190:193], v[114:117]
	v_mfma_f32_16x16x32_bf16 v[102:105], v[174:177], v[198:201], v[102:105]
	v_mfma_f32_16x16x32_bf16 v[98:101], v[182:185], v[198:201], v[98:101]
	v_mfma_f32_16x16x32_bf16 v[86:89], v[174:177], v[206:209], v[86:89]
	v_mfma_f32_16x16x32_bf16 v[82:85], v[182:185], v[206:209], v[82:85]
	v_mfma_f32_16x16x32_bf16 v[70:73], v[174:177], v[214:217], v[70:73]
	v_mfma_f32_16x16x32_bf16 v[66:69], v[182:185], v[214:217], v[66:69]
	v_mfma_f32_16x16x32_bf16 v[118:121], v[178:181], v[194:197], v[118:121]
	v_mfma_f32_16x16x32_bf16 v[114:117], v[186:189], v[194:197], v[114:117]
	v_mfma_f32_16x16x32_bf16 v[102:105], v[178:181], v[202:205], v[102:105]
	v_mfma_f32_16x16x32_bf16 v[98:101], v[186:189], v[202:205], v[98:101]
	v_mfma_f32_16x16x32_bf16 v[86:89], v[178:181], v[210:213], v[86:89]
	v_mfma_f32_16x16x32_bf16 v[82:85], v[186:189], v[210:213], v[82:85]
	v_mfma_f32_16x16x32_bf16 v[70:73], v[178:181], v[218:221], v[70:73]
	v_mfma_f32_16x16x32_bf16 v[66:69], v[186:189], v[218:221], v[66:69]
	s_setprio 0
	s_barrier
; #define PG8_STAGE(bufoff, gbase, voff) do { _Pragma("unroll") for (int _i = 0; _i < 2; ++_i) \
;         __builtin_amdgcn_global_load_lds((const __attribute__((address_space(1))) unsigned*)((const char*)(gbase) + (voff)[_i]), (LAS unsigned*)(lds + (bufoff) + ldsw + _i * 8192), 16, 0, 0); } while (0)
; #define PG8_LDA(dst, b, h) do { _Pragma("unroll") for (int m = 0; m < 4; ++m) _Pragma("unroll") for (int k = 0; k < 2; ++k) dst[m][k] = *(const LAS bf16x8*)(lds + PG8_SA(b, h) + aoff + m * 2048 + k * 1024); } while (0)
; #define PG8_MMA(ai, bj, At, Bt) do { __builtin_amdgcn_s_setprio(1); _Pragma("unroll") for (int m = 0; m < 4; ++m) _Pragma("unroll") for (int n = 0; n < 2; ++n) _Pragma("unroll") for (int k = 0; k < 2; ++k) \
;         acc[ai][bj][m][n] = __builtin_amdgcn_mfma_f32_16x16x32_bf16(Bt[n][k], At[m][k], acc[ai][bj][m][n], 0, 0, 0); __builtin_amdgcn_s_setprio(0); } while (0)
; #define PG8_WAIT_V(n) asm volatile("s_waitcnt vmcnt(" #n ")" ::: "memory")
; #define PG8_WAIT_L(n) asm volatile("s_waitcnt lgkmcnt(" #n ")" ::: "memory")
; #define PG8_BAR __builtin_amdgcn_s_barrier()
; #define PG8_SCHED __builtin_amdgcn_sched_barrier(0)
; template <class Epi, class SchedT, bool ALIGN_EPI, bool SP2>
; __device__ __forceinline__ void gemm_phase(LAS unsigned char* lds, const int ldk, const int nt, const SchedT& S, const Epi& E) {
;     ...
;             PG8_LDA(At, 1, 1); PG8_STAGE(PG8_SB(1, 0), b3, voffB); PG8_STAGE(PG8_SB(1, 1), b3 + hstepB, voffB); PG8_STAGE(PG8_SA(1, 0), a3, voffA);
;             PG8_WAIT_V(8); PG8_WAIT_L(0); PG8_BAR; PG8_MMA(1, 0, At, B0); PG8_MMA(1, 1, At, B1); PG8_BAR; PG8_SCHED;
;     __device__ __forceinline__ void operator()(f32x4 (&acc)[2][2][4][2], const Unit& u, int wr, int wc, int fr, int fq) const {
;         const int row0 = u.pm * BM + wr * 64 + fr, col0 = u.pn * BM + wc * 64 + 8 * fq;
; #pragma unroll
;         for (int ai = 0; ai < 2; ++ai)
; #pragma unroll
;             for (int m = 0; m < 4; ++m) {
;                 const int row = row0 + ai * HALF + m * 16; float sq = 0.f;
; #pragma unroll
;                 for (int bj = 0; bj < 2; ++bj) {
;                     const size_t off = (size_t)row * D + col0 + bj * 32;
;                     const u32x4 xw = *(const u32x4*)(xin + off);
	s_add_i32 s51, s51, s61
	v_lshl_add_u64 v[144:145], v[144:145], 0, s[24:25]
	s_mov_b32 m0, s51
	ds_read_b128 v[190:193], v149 offset:49152
	ds_read_b128 v[194:197], v149 offset:50176
	ds_read_b128 v[198:201], v149 offset:51200
	ds_read_b128 v[202:205], v149 offset:52224
	ds_read_b128 v[206:209], v149 offset:53248
	ds_read_b128 v[210:213], v149 offset:54272
	ds_read_b128 v[214:217], v149 offset:55296
	ds_read_b128 v[218:221], v149 offset:56320
	global_load_lds_dwordx4 v[144:145], off
	s_add_i32 m0, s51, 0x2000
	s_add_u32 s36, s36, 0x20080
	v_lshl_add_u64 v[144:145], v[222:223], 0, s[24:25]
	s_addc_u32 s37, s37, 0
	s_add_i32 s51, s53, s61
	global_load_lds_dwordx4 v[144:145], off
	v_lshl_add_u64 v[144:145], s[36:37], 0, v[0:1]
	s_mov_b32 m0, s51
	s_nop 0
	global_load_lds_dwordx4 v[144:145], off
	v_lshl_add_u64 v[144:145], s[36:37], 0, v[134:135]
	s_add_i32 m0, s51, 0x2000
	s_nop 0
	global_load_lds_dwordx4 v[144:145], off
	v_lshl_add_u64 v[144:145], v[224:225], 0, s[24:25]
	s_mov_b32 m0, s83
	s_nop 0
	global_load_lds_dwordx4 v[144:145], off
	v_lshl_add_u64 v[144:145], v[226:227], 0, s[24:25]
	s_mov_b32 m0, s84
	s_nop 0
	global_load_lds_dwordx4 v[144:145], off
	s_waitcnt vmcnt(8)
	s_waitcnt lgkmcnt(0)
	s_barrier
	s_setprio 1
	s_waitcnt lgkmcnt(0)
	v_mfma_f32_16x16x32_bf16 v[62:65], v[140:143], v[190:193], v[62:65]
	v_mfma_f32_16x16x32_bf16 v[58:61], v[154:157], v[190:193], v[58:61]
	v_mfma_f32_16x16x32_bf16 v[46:49], v[140:143], v[198:201], v[46:49]
	v_mfma_f32_16x16x32_bf16 v[42:45], v[154:157], v[198:201], v[42:45]
	v_mfma_f32_16x16x32_bf16 v[30:33], v[140:143], v[206:209], v[30:33]
	v_mfma_f32_16x16x32_bf16 v[26:29], v[154:157], v[206:209], v[26:29]
	v_mfma_f32_16x16x32_bf16 v[14:17], v[140:143], v[214:217], v[14:17]
	v_mfma_f32_16x16x32_bf16 v[10:13], v[154:157], v[214:217], v[10:13]
	v_mfma_f32_16x16x32_bf16 v[62:65], v[150:153], v[194:197], v[62:65]
	v_mfma_f32_16x16x32_bf16 v[58:61], v[158:161], v[194:197], v[58:61]
	v_mfma_f32_16x16x32_bf16 v[46:49], v[150:153], v[202:205], v[46:49]
	v_mfma_f32_16x16x32_bf16 v[42:45], v[158:161], v[202:205], v[42:45]
	v_mfma_f32_16x16x32_bf16 v[30:33], v[150:153], v[210:213], v[30:33]
	v_mfma_f32_16x16x32_bf16 v[26:29], v[158:161], v[210:213], v[26:29]
	v_mfma_f32_16x16x32_bf16 v[14:17], v[150:153], v[218:221], v[14:17]
	v_mfma_f32_16x16x32_bf16 v[10:13], v[158:161], v[218:221], v[10:13]
	s_setprio 0
	s_setprio 1
	v_mfma_f32_16x16x32_bf16 v[54:57], v[174:177], v[190:193], v[54:57]
	v_mfma_f32_16x16x32_bf16 v[50:53], v[182:185], v[190:193], v[50:53]
	v_mfma_f32_16x16x32_bf16 v[38:41], v[174:177], v[198:201], v[38:41]
	v_mfma_f32_16x16x32_bf16 v[34:37], v[182:185], v[198:201], v[34:37]
	v_mfma_f32_16x16x32_bf16 v[22:25], v[174:177], v[206:209], v[22:25]
	v_mfma_f32_16x16x32_bf16 v[18:21], v[182:185], v[206:209], v[18:21]
	v_mfma_f32_16x16x32_bf16 v[6:9], v[174:177], v[214:217], v[6:9]
	v_mfma_f32_16x16x32_bf16 v[2:5], v[182:185], v[214:217], v[2:5]
	v_mfma_f32_16x16x32_bf16 v[54:57], v[178:181], v[194:197], v[54:57]
	v_mfma_f32_16x16x32_bf16 v[50:53], v[186:189], v[194:197], v[50:53]
	v_mfma_f32_16x16x32_bf16 v[38:41], v[178:181], v[202:205], v[38:41]
	v_mfma_f32_16x16x32_bf16 v[34:37], v[186:189], v[202:205], v[34:37]
	v_mfma_f32_16x16x32_bf16 v[22:25], v[178:181], v[210:213], v[22:25]
	v_mfma_f32_16x16x32_bf16 v[18:21], v[186:189], v[210:213], v[18:21]
	v_mfma_f32_16x16x32_bf16 v[6:9], v[178:181], v[218:221], v[6:9]
	v_mfma_f32_16x16x32_bf16 v[2:5], v[186:189], v[218:221], v[2:5]
	s_setprio 0
	s_barrier
	s_add_i32 s22, s22, 2
	s_add_u32 s34, s34, 0x100
	s_addc_u32 s35, s35, 0
	s_add_u32 s13, s13, 0x100
	s_addc_u32 s20, s20, 0
	s_cmp_gt_u32 s22, 29
	s_cbranch_scc0 .LBB0_668
	v_lshl_add_u32 v142, s16, 8, v146
	v_lshl_or_b32 v140, s12, 8, v148
	v_lshlrev_b32_e32 v141, 12, v142
	v_lshl_add_u32 v150, v140, 1, v141
	v_add_u32_e32 v151, 0x10000, v150
	v_add_u32_e32 v152, 0x20000, v150
	v_add_u32_e32 v153, 0x30000, v150
	v_add_u32_e32 v154, 0x80000, v150
	v_add_u32_e32 v155, 0x90000, v150
	v_add_u32_e32 v156, 0xa0000, v150
	v_add_u32_e32 v157, 0xb0000, v150
	global_load_dwordx4 v[174:177], v150, s[42:43]
	global_load_dwordx4 v[178:181], v150, s[42:43] offset:64
	global_load_dwordx4 v[182:185], v151, s[42:43]
	global_load_dwordx4 v[186:189], v151, s[42:43] offset:64
	global_load_dwordx4 v[190:193], v152, s[42:43]
	global_load_dwordx4 v[194:197], v152, s[42:43] offset:64
	global_load_dwordx4 v[198:201], v153, s[42:43]
	global_load_dwordx4 v[202:205], v153, s[42:43] offset:64
	global_load_dwordx4 v[206:209], v154, s[42:43]
	global_load_dwordx4 v[210:213], v154, s[42:43] offset:64
	global_load_dwordx4 v[214:217], v155, s[42:43]
	global_load_dwordx4 v[218:221], v155, s[42:43] offset:64
	global_load_dwordx4 v[222:225], v156, s[42:43]
	global_load_dwordx4 v[226:229], v156, s[42:43] offset:64
	global_load_dwordx4 v[230:233], v157, s[42:43]
	global_load_dwordx4 v[234:237], v157, s[42:43] offset:64
	s_lshl_b32 s56, s12, 4
	s_lshl_b32 s22, s82, 2
	s_add_i32 s56, s56, s22
	v_lshl_add_u32 v158, v142, 7, s56
	v_add_u32_e32 v159, 0x1000, v158
	v_add_u32_e32 v160, 0x4000, v158
	v_add_u32_e32 v161, 0x5000, v158
	v_xor_b32_e32 v239, 16, v241
	v_xor_b32_e32 v252, 32, v241
	v_lshlrev_b32_e32 v239, 2, v239
	v_lshlrev_b32_e32 v252, 2, v252
	s_and_b64 vcc, exec, s[48:49]
	s_cbranch_vccz .LBB0_671
	s_barrier
; __device__ __forceinline__ float bf_lo(unsigned w) { return __uint_as_float(w << 16); }
; __device__ __forceinline__ float bf_hi(unsigned w) { return __uint_as_float(w & 0xffff0000u); }
; __device__ __forceinline__ u32x4 pack8(f32x4 a, f32x4 b) { u32x4 w; w.x = cvt_pk_bf16(a[0], a[1]); w.y = cvt_pk_bf16(a[2], a[3]); w.z = cvt_pk_bf16(b[0], b[1]); w.w = cvt_pk_bf16(b[2], b[3]); return w; }
;     __device__ __forceinline__ void operator()(f32x4 (&acc)[2][2][4][2], const Unit& u, int wr, int wc, int fr, int fq) const {
;     ...
;         for (int ai = 0; ai < 2; ++ai)
; #pragma unroll
;             for (int m = 0; m < 4; ++m) {
;                 const int row = row0 + ai * HALF + m * 16; float sq = 0.f;
; #pragma unroll
;                 for (int bj = 0; bj < 2; ++bj) {
;                     const size_t off = (size_t)row * D + col0 + bj * 32;
;                     const u32x4 xw = *(const u32x4*)(xin + off);
;                     const f32x4 v0 = acc[ai][bj][m][0] + (f32x4){bf_lo(xw.x), bf_hi(xw.x), bf_lo(xw.y), bf_hi(xw.y)}, v1 = acc[ai][bj][m][1] + (f32x4){bf_lo(xw.z), bf_hi(xw.z), bf_lo(xw.w), bf_hi(xw.w)};
;                     *(u32x4*)(xb + off) = pack8(v0, v1);
;                     sq += (v0[0] * v0[0] + v0[1] * v0[1]) + (v0[2] * v0[2] + v0[3] * v0[3]) + (v1[0] * v1[0] + v1[1] * v1[1]) + (v1[2] * v1[2] + v1[3] * v1[3]);
;                 }
.LBB0_671:
	s_waitcnt vmcnt(15)
	v_lshlrev_b32_e32 v246, 16, v174
	v_and_b32_e32 v247, 0xffff0000, v174
	v_lshlrev_b32_e32 v248, 16, v175
	v_and_b32_e32 v249, 0xffff0000, v175
	v_pk_add_f32 v[126:127], v[126:127], v[246:247]
	v_pk_add_f32 v[128:129], v[128:129], v[248:249]
	v_lshlrev_b32_e32 v246, 16, v176
	v_and_b32_e32 v247, 0xffff0000, v176
	v_lshlrev_b32_e32 v248, 16, v177
	v_and_b32_e32 v249, 0xffff0000, v177
	v_pk_add_f32 v[122:123], v[122:123], v[246:247]
	v_pk_add_f32 v[124:125], v[124:125], v[248:249]
	v_cvt_pk_bf16_f32 v174, v126, v127
	v_cvt_pk_bf16_f32 v175, v128, v129
	v_cvt_pk_bf16_f32 v176, v122, v123
	v_cvt_pk_bf16_f32 v177, v124, v125
	global_store_dwordx4 v150, v[174:177], s[44:45]
	v_pk_mul_f32 v[250:251], v[126:127], v[126:127]
	v_pk_fma_f32 v[250:251], v[128:129], v[128:129], v[250:251]
	v_pk_fma_f32 v[250:251], v[122:123], v[122:123], v[250:251]
	v_pk_fma_f32 v[250:251], v[124:125], v[124:125], v[250:251]
	s_waitcnt vmcnt(15)
	v_lshlrev_b32_e32 v246, 16, v178
	v_and_b32_e32 v247, 0xffff0000, v178
	v_lshlrev_b32_e32 v248, 16, v179
	v_and_b32_e32 v249, 0xffff0000, v179
	v_pk_add_f32 v[118:119], v[118:119], v[246:247]
	v_pk_add_f32 v[120:121], v[120:121], v[248:249]
	v_lshlrev_b32_e32 v246, 16, v180
	v_and_b32_e32 v247, 0xffff0000, v180
	v_lshlrev_b32_e32 v248, 16, v181
	v_and_b32_e32 v249, 0xffff0000, v181
	v_pk_add_f32 v[114:115], v[114:115], v[246:247]
	v_pk_add_f32 v[116:117], v[116:117], v[248:249]
	v_cvt_pk_bf16_f32 v178, v118, v119
	v_cvt_pk_bf16_f32 v179, v120, v121
	v_cvt_pk_bf16_f32 v180, v114, v115
	v_cvt_pk_bf16_f32 v181, v116, v117
	global_store_dwordx4 v150, v[178:181], s[44:45] offset:64
	v_pk_fma_f32 v[250:251], v[118:119], v[118:119], v[250:251]
	v_pk_fma_f32 v[250:251], v[120:121], v[120:121], v[250:251]
	v_pk_fma_f32 v[250:251], v[114:115], v[114:115], v[250:251]
	v_pk_fma_f32 v[250:251], v[116:117], v[116:117], v[250:251]
	v_add_f32_e32 v140, v250, v251
	s_waitcnt vmcnt(15)
	v_lshlrev_b32_e32 v246, 16, v182
	v_and_b32_e32 v247, 0xffff0000, v182
	v_lshlrev_b32_e32 v248, 16, v183
	v_and_b32_e32 v249, 0xffff0000, v183
	v_pk_add_f32 v[110:111], v[110:111], v[246:247]
	v_pk_add_f32 v[112:113], v[112:113], v[248:249]
	v_lshlrev_b32_e32 v246, 16, v184
	v_and_b32_e32 v247, 0xffff0000, v184
	v_lshlrev_b32_e32 v248, 16, v185
	v_and_b32_e32 v249, 0xffff0000, v185
	v_pk_add_f32 v[106:107], v[106:107], v[246:247]
	v_pk_add_f32 v[108:109], v[108:109], v[248:249]
	v_cvt_pk_bf16_f32 v182, v110, v111
	v_cvt_pk_bf16_f32 v183, v112, v113
	v_cvt_pk_bf16_f32 v184, v106, v107
	v_cvt_pk_bf16_f32 v185, v108, v109
	global_store_dwordx4 v151, v[182:185], s[44:45]
	v_pk_mul_f32 v[250:251], v[110:111], v[110:111]
	v_pk_fma_f32 v[250:251], v[112:113], v[112:113], v[250:251]
	v_pk_fma_f32 v[250:251], v[106:107], v[106:107], v[250:251]
	v_pk_fma_f32 v[250:251], v[108:109], v[108:109], v[250:251]
	s_waitcnt vmcnt(15)
	v_lshlrev_b32_e32 v246, 16, v186
	v_and_b32_e32 v247, 0xffff0000, v186
	v_lshlrev_b32_e32 v248, 16, v187
	v_and_b32_e32 v249, 0xffff0000, v187
	v_pk_add_f32 v[102:103], v[102:103], v[246:247]
	v_pk_add_f32 v[104:105], v[104:105], v[248:249]
	v_lshlrev_b32_e32 v246, 16, v188
	v_and_b32_e32 v247, 0xffff0000, v188
	v_lshlrev_b32_e32 v248, 16, v189
	v_and_b32_e32 v249, 0xffff0000, v189
	v_pk_add_f32 v[98:99], v[98:99], v[246:247]
	v_pk_add_f32 v[100:101], v[100:101], v[248:249]
	v_cvt_pk_bf16_f32 v186, v102, v103
	v_cvt_pk_bf16_f32 v187, v104, v105
	v_cvt_pk_bf16_f32 v188, v98, v99
	v_cvt_pk_bf16_f32 v189, v100, v101
	global_store_dwordx4 v151, v[186:189], s[44:45] offset:64
	v_pk_fma_f32 v[250:251], v[102:103], v[102:103], v[250:251]
	v_pk_fma_f32 v[250:251], v[104:105], v[104:105], v[250:251]
	v_pk_fma_f32 v[250:251], v[98:99], v[98:99], v[250:251]
	v_pk_fma_f32 v[250:251], v[100:101], v[100:101], v[250:251]
	v_add_f32_e32 v141, v250, v251
	s_waitcnt vmcnt(15)
	v_lshlrev_b32_e32 v246, 16, v190
	v_and_b32_e32 v247, 0xffff0000, v190
	v_lshlrev_b32_e32 v248, 16, v191
	v_and_b32_e32 v249, 0xffff0000, v191
	v_pk_add_f32 v[94:95], v[94:95], v[246:247]
	v_pk_add_f32 v[96:97], v[96:97], v[248:249]
	v_lshlrev_b32_e32 v246, 16, v192
	v_and_b32_e32 v247, 0xffff0000, v192
	v_lshlrev_b32_e32 v248, 16, v193
	v_and_b32_e32 v249, 0xffff0000, v193
	v_pk_add_f32 v[90:91], v[90:91], v[246:247]
	v_pk_add_f32 v[92:93], v[92:93], v[248:249]
	v_cvt_pk_bf16_f32 v190, v94, v95
	v_cvt_pk_bf16_f32 v191, v96, v97
	v_cvt_pk_bf16_f32 v192, v90, v91
	v_cvt_pk_bf16_f32 v193, v92, v93
	global_store_dwordx4 v152, v[190:193], s[44:45]
	v_pk_mul_f32 v[250:251], v[94:95], v[94:95]
	v_pk_fma_f32 v[250:251], v[96:97], v[96:97], v[250:251]
	v_pk_fma_f32 v[250:251], v[90:91], v[90:91], v[250:251]
	v_pk_fma_f32 v[250:251], v[92:93], v[92:93], v[250:251]
	s_waitcnt vmcnt(15)
	v_lshlrev_b32_e32 v246, 16, v194
	v_and_b32_e32 v247, 0xffff0000, v194
	v_lshlrev_b32_e32 v248, 16, v195
	v_and_b32_e32 v249, 0xffff0000, v195
	v_pk_add_f32 v[86:87], v[86:87], v[246:247]
	v_pk_add_f32 v[88:89], v[88:89], v[248:249]
	v_lshlrev_b32_e32 v246, 16, v196
	v_and_b32_e32 v247, 0xffff0000, v196
	v_lshlrev_b32_e32 v248, 16, v197
	v_and_b32_e32 v249, 0xffff0000, v197
	v_pk_add_f32 v[82:83], v[82:83], v[246:247]
	v_pk_add_f32 v[84:85], v[84:85], v[248:249]
	v_cvt_pk_bf16_f32 v194, v86, v87
	v_cvt_pk_bf16_f32 v195, v88, v89
	v_cvt_pk_bf16_f32 v196, v82, v83
	v_cvt_pk_bf16_f32 v197, v84, v85
	global_store_dwordx4 v152, v[194:197], s[44:45] offset:64
	v_pk_fma_f32 v[250:251], v[86:87], v[86:87], v[250:251]
	v_pk_fma_f32 v[250:251], v[88:89], v[88:89], v[250:251]
	v_pk_fma_f32 v[250:251], v[82:83], v[82:83], v[250:251]
	v_pk_fma_f32 v[250:251], v[84:85], v[84:85], v[250:251]
	v_add_f32_e32 v142, v250, v251
	s_waitcnt vmcnt(15)
; __device__ __forceinline__ float bf_lo(unsigned w) { return __uint_as_float(w << 16); }
; __device__ __forceinline__ float bf_hi(unsigned w) { return __uint_as_float(w & 0xffff0000u); }
; __device__ __forceinline__ u32x4 pack8(f32x4 a, f32x4 b) { u32x4 w; w.x = cvt_pk_bf16(a[0], a[1]); w.y = cvt_pk_bf16(a[2], a[3]); w.z = cvt_pk_bf16(b[0], b[1]); w.w = cvt_pk_bf16(b[2], b[3]); return w; }
;     __device__ __forceinline__ void operator()(f32x4 (&acc)[2][2][4][2], const Unit& u, int wr, int wc, int fr, int fq) const {
;     ...
;         for (int ai = 0; ai < 2; ++ai)
; #pragma unroll
;             for (int m = 0; m < 4; ++m) {
;                 const int row = row0 + ai * HALF + m * 16; float sq = 0.f;
; #pragma unroll
;                 for (int bj = 0; bj < 2; ++bj) {
;                     const size_t off = (size_t)row * D + col0 + bj * 32;
;                     const u32x4 xw = *(const u32x4*)(xin + off);
;                     const f32x4 v0 = acc[ai][bj][m][0] + (f32x4){bf_lo(xw.x), bf_hi(xw.x), bf_lo(xw.y), bf_hi(xw.y)}, v1 = acc[ai][bj][m][1] + (f32x4){bf_lo(xw.z), bf_hi(xw.z), bf_lo(xw.w), bf_hi(xw.w)};
;                     *(u32x4*)(xb + off) = pack8(v0, v1);
;                     sq += (v0[0] * v0[0] + v0[1] * v0[1]) + (v0[2] * v0[2] + v0[3] * v0[3]) + (v1[0] * v1[0] + v1[1] * v1[1]) + (v1[2] * v1[2] + v1[3] * v1[3]);
;                 }
	v_lshlrev_b32_e32 v246, 16, v198
	v_and_b32_e32 v247, 0xffff0000, v198
	v_lshlrev_b32_e32 v248, 16, v199
	v_and_b32_e32 v249, 0xffff0000, v199
	v_pk_add_f32 v[78:79], v[78:79], v[246:247]
	v_pk_add_f32 v[80:81], v[80:81], v[248:249]
	v_lshlrev_b32_e32 v246, 16, v200
	v_and_b32_e32 v247, 0xffff0000, v200
	v_lshlrev_b32_e32 v248, 16, v201
	v_and_b32_e32 v249, 0xffff0000, v201
	v_pk_add_f32 v[74:75], v[74:75], v[246:247]
	v_pk_add_f32 v[76:77], v[76:77], v[248:249]
	v_cvt_pk_bf16_f32 v198, v78, v79
	v_cvt_pk_bf16_f32 v199, v80, v81
	v_cvt_pk_bf16_f32 v200, v74, v75
	v_cvt_pk_bf16_f32 v201, v76, v77
	global_store_dwordx4 v153, v[198:201], s[44:45]
	v_pk_mul_f32 v[250:251], v[78:79], v[78:79]
	v_pk_fma_f32 v[250:251], v[80:81], v[80:81], v[250:251]
	v_pk_fma_f32 v[250:251], v[74:75], v[74:75], v[250:251]
	v_pk_fma_f32 v[250:251], v[76:77], v[76:77], v[250:251]
	s_waitcnt vmcnt(15)
	v_lshlrev_b32_e32 v246, 16, v202
	v_and_b32_e32 v247, 0xffff0000, v202
	v_lshlrev_b32_e32 v248, 16, v203
	v_and_b32_e32 v249, 0xffff0000, v203
	v_pk_add_f32 v[70:71], v[70:71], v[246:247]
	v_pk_add_f32 v[72:73], v[72:73], v[248:249]
	v_lshlrev_b32_e32 v246, 16, v204
	v_and_b32_e32 v247, 0xffff0000, v204
	v_lshlrev_b32_e32 v248, 16, v205
	v_and_b32_e32 v249, 0xffff0000, v205
	v_pk_add_f32 v[66:67], v[66:67], v[246:247]
	v_pk_add_f32 v[68:69], v[68:69], v[248:249]
	v_cvt_pk_bf16_f32 v202, v70, v71
	v_cvt_pk_bf16_f32 v203, v72, v73
	v_cvt_pk_bf16_f32 v204, v66, v67
	v_cvt_pk_bf16_f32 v205, v68, v69
	global_store_dwordx4 v153, v[202:205], s[44:45] offset:64
	v_pk_fma_f32 v[250:251], v[70:71], v[70:71], v[250:251]
	v_pk_fma_f32 v[250:251], v[72:73], v[72:73], v[250:251]
	v_pk_fma_f32 v[250:251], v[66:67], v[66:67], v[250:251]
	v_pk_fma_f32 v[250:251], v[68:69], v[68:69], v[250:251]
	v_add_f32_e32 v143, v250, v251
	s_waitcnt vmcnt(15)
	v_lshlrev_b32_e32 v246, 16, v206
	v_and_b32_e32 v247, 0xffff0000, v206
	v_lshlrev_b32_e32 v248, 16, v207
	v_and_b32_e32 v249, 0xffff0000, v207
	v_pk_add_f32 v[62:63], v[62:63], v[246:247]
	v_pk_add_f32 v[64:65], v[64:65], v[248:249]
	v_lshlrev_b32_e32 v246, 16, v208
	v_and_b32_e32 v247, 0xffff0000, v208
	v_lshlrev_b32_e32 v248, 16, v209
	v_and_b32_e32 v249, 0xffff0000, v209
	v_pk_add_f32 v[58:59], v[58:59], v[246:247]
	v_pk_add_f32 v[60:61], v[60:61], v[248:249]
	v_cvt_pk_bf16_f32 v206, v62, v63
	v_cvt_pk_bf16_f32 v207, v64, v65
	v_cvt_pk_bf16_f32 v208, v58, v59
	v_cvt_pk_bf16_f32 v209, v60, v61
	global_store_dwordx4 v154, v[206:209], s[44:45]
	v_pk_mul_f32 v[250:251], v[62:63], v[62:63]
	v_pk_fma_f32 v[250:251], v[64:65], v[64:65], v[250:251]
	v_pk_fma_f32 v[250:251], v[58:59], v[58:59], v[250:251]
	v_pk_fma_f32 v[250:251], v[60:61], v[60:61], v[250:251]
	s_waitcnt vmcnt(15)
	v_lshlrev_b32_e32 v246, 16, v210
	v_and_b32_e32 v247, 0xffff0000, v210
	v_lshlrev_b32_e32 v248, 16, v211
	v_and_b32_e32 v249, 0xffff0000, v211
	v_pk_add_f32 v[54:55], v[54:55], v[246:247]
	v_pk_add_f32 v[56:57], v[56:57], v[248:249]
	v_lshlrev_b32_e32 v246, 16, v212
	v_and_b32_e32 v247, 0xffff0000, v212
	v_lshlrev_b32_e32 v248, 16, v213
	v_and_b32_e32 v249, 0xffff0000, v213
	v_pk_add_f32 v[50:51], v[50:51], v[246:247]
	v_pk_add_f32 v[52:53], v[52:53], v[248:249]
	v_cvt_pk_bf16_f32 v210, v54, v55
	v_cvt_pk_bf16_f32 v211, v56, v57
	v_cvt_pk_bf16_f32 v212, v50, v51
	v_cvt_pk_bf16_f32 v213, v52, v53
	global_store_dwordx4 v154, v[210:213], s[44:45] offset:64
	v_pk_fma_f32 v[250:251], v[54:55], v[54:55], v[250:251]
	v_pk_fma_f32 v[250:251], v[56:57], v[56:57], v[250:251]
	v_pk_fma_f32 v[250:251], v[50:51], v[50:51], v[250:251]
	v_pk_fma_f32 v[250:251], v[52:53], v[52:53], v[250:251]
	v_add_f32_e32 v144, v250, v251
	s_waitcnt vmcnt(15)
	v_lshlrev_b32_e32 v246, 16, v214
	v_and_b32_e32 v247, 0xffff0000, v214
	v_lshlrev_b32_e32 v248, 16, v215
	v_and_b32_e32 v249, 0xffff0000, v215
	v_pk_add_f32 v[46:47], v[46:47], v[246:247]
	v_pk_add_f32 v[48:49], v[48:49], v[248:249]
	v_lshlrev_b32_e32 v246, 16, v216
	v_and_b32_e32 v247, 0xffff0000, v216
	v_lshlrev_b32_e32 v248, 16, v217
	v_and_b32_e32 v249, 0xffff0000, v217
	v_pk_add_f32 v[42:43], v[42:43], v[246:247]
	v_pk_add_f32 v[44:45], v[44:45], v[248:249]
	v_cvt_pk_bf16_f32 v214, v46, v47
	v_cvt_pk_bf16_f32 v215, v48, v49
	v_cvt_pk_bf16_f32 v216, v42, v43
	v_cvt_pk_bf16_f32 v217, v44, v45
	global_store_dwordx4 v155, v[214:217], s[44:45]
	v_pk_mul_f32 v[250:251], v[46:47], v[46:47]
	v_pk_fma_f32 v[250:251], v[48:49], v[48:49], v[250:251]
	v_pk_fma_f32 v[250:251], v[42:43], v[42:43], v[250:251]
	v_pk_fma_f32 v[250:251], v[44:45], v[44:45], v[250:251]
	s_waitcnt vmcnt(15)
	v_lshlrev_b32_e32 v246, 16, v218
	v_and_b32_e32 v247, 0xffff0000, v218
	v_lshlrev_b32_e32 v248, 16, v219
	v_and_b32_e32 v249, 0xffff0000, v219
	v_pk_add_f32 v[38:39], v[38:39], v[246:247]
	v_pk_add_f32 v[40:41], v[40:41], v[248:249]
	v_lshlrev_b32_e32 v246, 16, v220
	v_and_b32_e32 v247, 0xffff0000, v220
	v_lshlrev_b32_e32 v248, 16, v221
	v_and_b32_e32 v249, 0xffff0000, v221
	v_pk_add_f32 v[34:35], v[34:35], v[246:247]
	v_pk_add_f32 v[36:37], v[36:37], v[248:249]
	v_cvt_pk_bf16_f32 v218, v38, v39
	v_cvt_pk_bf16_f32 v219, v40, v41
	v_cvt_pk_bf16_f32 v220, v34, v35
	v_cvt_pk_bf16_f32 v221, v36, v37
	global_store_dwordx4 v155, v[218:221], s[44:45] offset:64
	v_pk_fma_f32 v[250:251], v[38:39], v[38:39], v[250:251]
	v_pk_fma_f32 v[250:251], v[40:41], v[40:41], v[250:251]
	v_pk_fma_f32 v[250:251], v[34:35], v[34:35], v[250:251]
	v_pk_fma_f32 v[250:251], v[36:37], v[36:37], v[250:251]
	v_add_f32_e32 v145, v250, v251
	s_waitcnt vmcnt(15)
; __device__ __forceinline__ float bf_lo(unsigned w) { return __uint_as_float(w << 16); }
; __device__ __forceinline__ float bf_hi(unsigned w) { return __uint_as_float(w & 0xffff0000u); }
; __device__ __forceinline__ u32x4 pack8(f32x4 a, f32x4 b) { u32x4 w; w.x = cvt_pk_bf16(a[0], a[1]); w.y = cvt_pk_bf16(a[2], a[3]); w.z = cvt_pk_bf16(b[0], b[1]); w.w = cvt_pk_bf16(b[2], b[3]); return w; }
;     __device__ __forceinline__ void operator()(f32x4 (&acc)[2][2][4][2], const Unit& u, int wr, int wc, int fr, int fq) const {
;     ...
;                 for (int bj = 0; bj < 2; ++bj) {
;                     const size_t off = (size_t)row * D + col0 + bj * 32;
;                     const u32x4 xw = *(const u32x4*)(xin + off);
;                     const f32x4 v0 = acc[ai][bj][m][0] + (f32x4){bf_lo(xw.x), bf_hi(xw.x), bf_lo(xw.y), bf_hi(xw.y)}, v1 = acc[ai][bj][m][1] + (f32x4){bf_lo(xw.z), bf_hi(xw.z), bf_lo(xw.w), bf_hi(xw.w)};
;                     *(u32x4*)(xb + off) = pack8(v0, v1);
;                     sq += (v0[0] * v0[0] + v0[1] * v0[1]) + (v0[2] * v0[2] + v0[3] * v0[3]) + (v1[0] * v1[0] + v1[1] * v1[1]) + (v1[2] * v1[2] + v1[3] * v1[3]);
;                 }
;                 sq += __shfl_xor(sq, 16); sq += __shfl_xor(sq, 32);
;                 if (fq == 0) ss[(size_t)row * 32 + u.pn * 4 + wc] = sq;
	v_lshlrev_b32_e32 v246, 16, v222
	v_and_b32_e32 v247, 0xffff0000, v222
	v_lshlrev_b32_e32 v248, 16, v223
	v_and_b32_e32 v249, 0xffff0000, v223
	v_pk_add_f32 v[30:31], v[30:31], v[246:247]
	v_pk_add_f32 v[32:33], v[32:33], v[248:249]
	v_lshlrev_b32_e32 v246, 16, v224
	v_and_b32_e32 v247, 0xffff0000, v224
	v_lshlrev_b32_e32 v248, 16, v225
	v_and_b32_e32 v249, 0xffff0000, v225
	v_pk_add_f32 v[26:27], v[26:27], v[246:247]
	v_pk_add_f32 v[28:29], v[28:29], v[248:249]
	v_cvt_pk_bf16_f32 v222, v30, v31
	v_cvt_pk_bf16_f32 v223, v32, v33
	v_cvt_pk_bf16_f32 v224, v26, v27
	v_cvt_pk_bf16_f32 v225, v28, v29
	global_store_dwordx4 v156, v[222:225], s[44:45]
	v_pk_mul_f32 v[250:251], v[30:31], v[30:31]
	v_pk_fma_f32 v[250:251], v[32:33], v[32:33], v[250:251]
	v_pk_fma_f32 v[250:251], v[26:27], v[26:27], v[250:251]
	v_pk_fma_f32 v[250:251], v[28:29], v[28:29], v[250:251]
	s_waitcnt vmcnt(15)
	v_lshlrev_b32_e32 v246, 16, v226
	v_and_b32_e32 v247, 0xffff0000, v226
	v_lshlrev_b32_e32 v248, 16, v227
	v_and_b32_e32 v249, 0xffff0000, v227
	v_pk_add_f32 v[22:23], v[22:23], v[246:247]
	v_pk_add_f32 v[24:25], v[24:25], v[248:249]
	v_lshlrev_b32_e32 v246, 16, v228
	v_and_b32_e32 v247, 0xffff0000, v228
	v_lshlrev_b32_e32 v248, 16, v229
	v_and_b32_e32 v249, 0xffff0000, v229
	v_pk_add_f32 v[18:19], v[18:19], v[246:247]
	v_pk_add_f32 v[20:21], v[20:21], v[248:249]
	v_cvt_pk_bf16_f32 v226, v22, v23
	v_cvt_pk_bf16_f32 v227, v24, v25
	v_cvt_pk_bf16_f32 v228, v18, v19
	v_cvt_pk_bf16_f32 v229, v20, v21
	global_store_dwordx4 v156, v[226:229], s[44:45] offset:64
	v_pk_fma_f32 v[250:251], v[22:23], v[22:23], v[250:251]
	v_pk_fma_f32 v[250:251], v[24:25], v[24:25], v[250:251]
	v_pk_fma_f32 v[250:251], v[18:19], v[18:19], v[250:251]
	v_pk_fma_f32 v[250:251], v[20:21], v[20:21], v[250:251]
	v_add_f32_e32 v162, v250, v251
	s_waitcnt vmcnt(15)
	v_lshlrev_b32_e32 v246, 16, v230
	v_and_b32_e32 v247, 0xffff0000, v230
	v_lshlrev_b32_e32 v248, 16, v231
	v_and_b32_e32 v249, 0xffff0000, v231
	v_pk_add_f32 v[14:15], v[14:15], v[246:247]
	v_pk_add_f32 v[16:17], v[16:17], v[248:249]
	v_lshlrev_b32_e32 v246, 16, v232
	v_and_b32_e32 v247, 0xffff0000, v232
	v_lshlrev_b32_e32 v248, 16, v233
	v_and_b32_e32 v249, 0xffff0000, v233
	v_pk_add_f32 v[10:11], v[10:11], v[246:247]
	v_pk_add_f32 v[12:13], v[12:13], v[248:249]
	v_cvt_pk_bf16_f32 v230, v14, v15
	v_cvt_pk_bf16_f32 v231, v16, v17
	v_cvt_pk_bf16_f32 v232, v10, v11
	v_cvt_pk_bf16_f32 v233, v12, v13
	global_store_dwordx4 v157, v[230:233], s[44:45]
	v_pk_mul_f32 v[250:251], v[14:15], v[14:15]
	v_pk_fma_f32 v[250:251], v[16:17], v[16:17], v[250:251]
	v_pk_fma_f32 v[250:251], v[10:11], v[10:11], v[250:251]
	v_pk_fma_f32 v[250:251], v[12:13], v[12:13], v[250:251]
	s_waitcnt vmcnt(15)
	v_lshlrev_b32_e32 v246, 16, v234
	v_and_b32_e32 v247, 0xffff0000, v234
	v_lshlrev_b32_e32 v248, 16, v235
	v_and_b32_e32 v249, 0xffff0000, v235
	v_pk_add_f32 v[6:7], v[6:7], v[246:247]
	v_pk_add_f32 v[8:9], v[8:9], v[248:249]
	v_lshlrev_b32_e32 v246, 16, v236
	v_and_b32_e32 v247, 0xffff0000, v236
	v_lshlrev_b32_e32 v248, 16, v237
	v_and_b32_e32 v249, 0xffff0000, v237
	v_pk_add_f32 v[2:3], v[2:3], v[246:247]
	v_pk_add_f32 v[4:5], v[4:5], v[248:249]
	v_cvt_pk_bf16_f32 v234, v6, v7
	v_cvt_pk_bf16_f32 v235, v8, v9
	v_cvt_pk_bf16_f32 v236, v2, v3
	v_cvt_pk_bf16_f32 v237, v4, v5
	global_store_dwordx4 v157, v[234:237], s[44:45] offset:64
	v_pk_fma_f32 v[250:251], v[6:7], v[6:7], v[250:251]
	v_pk_fma_f32 v[250:251], v[8:9], v[8:9], v[250:251]
	v_pk_fma_f32 v[250:251], v[2:3], v[2:3], v[250:251]
	v_pk_fma_f32 v[250:251], v[4:5], v[4:5], v[250:251]
	v_add_f32_e32 v238, v250, v251
	ds_bpermute_b32 v174, v239, v140
	ds_bpermute_b32 v175, v239, v141
	ds_bpermute_b32 v176, v239, v142
	ds_bpermute_b32 v177, v239, v143
	ds_bpermute_b32 v178, v239, v144
	ds_bpermute_b32 v179, v239, v145
	ds_bpermute_b32 v180, v239, v162
	ds_bpermute_b32 v181, v239, v238
	s_waitcnt lgkmcnt(0)
	v_add_f32_e32 v140, v140, v174
	v_add_f32_e32 v141, v141, v175
	v_add_f32_e32 v142, v142, v176
	v_add_f32_e32 v143, v143, v177
	v_add_f32_e32 v144, v144, v178
	v_add_f32_e32 v145, v145, v179
	v_add_f32_e32 v162, v162, v180
	v_add_f32_e32 v238, v238, v181
	ds_bpermute_b32 v174, v252, v140
	ds_bpermute_b32 v175, v252, v141
	ds_bpermute_b32 v176, v252, v142
	ds_bpermute_b32 v177, v252, v143
	ds_bpermute_b32 v178, v252, v144
	ds_bpermute_b32 v179, v252, v145
	ds_bpermute_b32 v180, v252, v162
	ds_bpermute_b32 v181, v252, v238
	s_waitcnt lgkmcnt(0)
	v_add_f32_e32 v140, v140, v174
	v_add_f32_e32 v141, v141, v175
	v_add_f32_e32 v142, v142, v176
	v_add_f32_e32 v143, v143, v177
	v_add_f32_e32 v144, v144, v178
	v_add_f32_e32 v145, v145, v179
	v_add_f32_e32 v162, v162, v180
	v_add_f32_e32 v238, v238, v181
	s_and_saveexec_b64 s[12:13], s[38:39]
	global_store_dword v158, v140, s[46:47]
	global_store_dword v158, v141, s[46:47] offset:2048
	global_store_dword v159, v142, s[46:47]
	global_store_dword v159, v143, s[46:47] offset:2048
	global_store_dword v160, v144, s[46:47]
	global_store_dword v160, v145, s[46:47] offset:2048
	global_store_dword v161, v162, s[46:47]
	global_store_dword v161, v238, s[46:47] offset:2048
	s_mov_b32 s86, 0x20000
	s_mov_b32 s87, 0x28000
	s_or_b64 exec, exec, s[12:13]
	s_and_b64 vcc, exec, s[40:41]
	s_mov_b64 s[12:13], -1
	s_cbranch_vccnz .LBB0_662
	s_andn2_b64 vcc, exec, s[18:19]
	s_cbranch_vccnz .LBB0_661
	s_barrier
	s_branch .LBB0_661

; #define PG8_STAGE(bufoff, gbase, voff) do { _Pragma("unroll") for (int _i = 0; _i < 2; ++_i) \
;         __builtin_amdgcn_global_load_lds((const __attribute__((address_space(1))) unsigned*)((const char*)(gbase) + (voff)[_i]), (LAS unsigned*)(lds + (bufoff) + ldsw + _i * 8192), 16, 0, 0); } while (0)
; #define PG8_LDA(dst, b, h) do { _Pragma("unroll") for (int m = 0; m < 4; ++m) _Pragma("unroll") for (int k = 0; k < 2; ++k) dst[m][k] = *(const LAS bf16x8*)(lds + PG8_SA(b, h) + aoff + m * 2048 + k * 1024); } while (0)
; #define PG8_LDB(dst, b, h) do { _Pragma("unroll") for (int n = 0; n < 2; ++n) _Pragma("unroll") for (int k = 0; k < 2; ++k) dst[n][k] = *(const LAS bf16x8*)(lds + PG8_SB(b, h) + boff + n * 2048 + k * 1024); } while (0)
; #define PG8_MMA(ai, bj, At, Bt) do { __builtin_amdgcn_s_setprio(1); _Pragma("unroll") for (int m = 0; m < 4; ++m) _Pragma("unroll") for (int n = 0; n < 2; ++n) _Pragma("unroll") for (int k = 0; k < 2; ++k) \
;         acc[ai][bj][m][n] = __builtin_amdgcn_mfma_f32_16x16x32_bf16(Bt[n][k], At[m][k], acc[ai][bj][m][n], 0, 0, 0); __builtin_amdgcn_s_setprio(0); } while (0)
; #define PG8_WAIT_V(n) asm volatile("s_waitcnt vmcnt(" #n ")" ::: "memory")
; #define PG8_WAIT_L(n) asm volatile("s_waitcnt lgkmcnt(" #n ")" ::: "memory")
; #define PG8_BAR __builtin_amdgcn_s_barrier()
; #define PG8_SCHED __builtin_amdgcn_sched_barrier(0)
; template <class Epi, class SchedT, bool ALIGN_EPI, bool SP2>
; __device__ __forceinline__ void gemm_phase(LAS unsigned char* lds, const int ldk, const int nt, const SchedT& S, const Epi& E) {
;     ...
;         for (int t = 0; t < nt; t += 2) {
;             const bool last = (t == nt - 2);
;             const char* a1 = cA + (size_t)(t + 1) * kstep;
;             const char* a2 = last ? nA : cA + (size_t)(t + 2) * kstep; const char* b2 = last ? nB : cB + (size_t)(t + 2) * kstep;
;             const char* a3 = a2 + kstep; const char* b3 = b2 + kstep;
;             if constexpr (SP2) {
;             PG8_LDB(B0, 0, 0); PG8_LDB(B1, 0, 1); PG8_SCHED; PG8_LDA(At, 0, 0); PG8_STAGE(PG8_SA(1, 1), a1 + hstep, voffA);
;             PG8_WAIT_V(8); PG8_WAIT_L(0); PG8_BAR; PG8_MMA(0, 0, At, B0); PG8_MMA(0, 1, At, B1); PG8_BAR; PG8_SCHED;
;             PG8_LDA(At, 0, 1); PG8_STAGE(PG8_SB(0, 0), b2, voffB); PG8_STAGE(PG8_SB(0, 1), b2 + hstepB, voffB); PG8_STAGE(PG8_SA(0, 0), a2, voffA);
.LBB0_948:
	s_add_u32 s16, s12, 0x100
	s_addc_u32 s17, s13, 0
	s_add_i32 s64, 0, 0x10000
	s_cmpk_eq_i32 s83, 0x52
	s_cselect_b32 s47, s1, s17
	s_cselect_b32 s46, s0, s16
	v_add_u32_e32 v144, s64, v147
	s_cselect_b32 s45, s43, s82
	s_cselect_b32 s44, s42, s81
	s_add_i32 s65, 0, 0x14000
	ds_read_b128 v[140:143], v144
	ds_read_b128 v[150:153], v144 offset:1024
	ds_read_b128 v[154:157], v144 offset:2048
	ds_read_b128 v[158:161], v144 offset:3072
	v_add_u32_e32 v144, s65, v147
	ds_read_b128 v[174:177], v144
	ds_read_b128 v[178:181], v144 offset:1024
	ds_read_b128 v[182:185], v144 offset:2048
	ds_read_b128 v[186:189], v144 offset:3072
	v_lshl_add_u64 v[144:145], s[12:13], 0, v[136:137]
	s_add_i32 m0, s53, 0xc000
	ds_read_b128 v[190:193], v149
	ds_read_b128 v[194:197], v149 offset:1024
	ds_read_b128 v[198:201], v149 offset:2048
	ds_read_b128 v[202:205], v149 offset:3072
	ds_read_b128 v[206:209], v149 offset:4096
	ds_read_b128 v[210:213], v149 offset:5120
	ds_read_b128 v[214:217], v149 offset:6144
	ds_read_b128 v[218:221], v149 offset:7168
	global_load_lds_dwordx4 v[144:145], off
	v_lshl_add_u64 v[144:145], s[12:13], 0, v[138:139]
	s_add_i32 m0, s53, 0xe000
	s_nop 0
	global_load_lds_dwordx4 v[144:145], off
	s_waitcnt vmcnt(8)
	s_waitcnt lgkmcnt(0)
	s_barrier
	s_setprio 1
	s_waitcnt lgkmcnt(0)
	v_mfma_f32_16x16x32_bf16 v[126:129], v[140:143], v[190:193], v[126:129]
	v_mfma_f32_16x16x32_bf16 v[122:125], v[154:157], v[190:193], v[122:125]
	v_mfma_f32_16x16x32_bf16 v[110:113], v[140:143], v[198:201], v[110:113]
	v_mfma_f32_16x16x32_bf16 v[106:109], v[154:157], v[198:201], v[106:109]
	v_mfma_f32_16x16x32_bf16 v[94:97], v[140:143], v[206:209], v[94:97]
	v_mfma_f32_16x16x32_bf16 v[90:93], v[154:157], v[206:209], v[90:93]
	v_mfma_f32_16x16x32_bf16 v[78:81], v[140:143], v[214:217], v[78:81]
	v_mfma_f32_16x16x32_bf16 v[74:77], v[154:157], v[214:217], v[74:77]
	v_mfma_f32_16x16x32_bf16 v[126:129], v[150:153], v[194:197], v[126:129]
	v_mfma_f32_16x16x32_bf16 v[122:125], v[158:161], v[194:197], v[122:125]
	v_mfma_f32_16x16x32_bf16 v[110:113], v[150:153], v[202:205], v[110:113]
	v_mfma_f32_16x16x32_bf16 v[106:109], v[158:161], v[202:205], v[106:109]
	v_mfma_f32_16x16x32_bf16 v[94:97], v[150:153], v[210:213], v[94:97]
	v_mfma_f32_16x16x32_bf16 v[90:93], v[158:161], v[210:213], v[90:93]
	v_mfma_f32_16x16x32_bf16 v[78:81], v[150:153], v[218:221], v[78:81]
	v_mfma_f32_16x16x32_bf16 v[74:77], v[158:161], v[218:221], v[74:77]
	s_setprio 0
	s_setprio 1
	v_mfma_f32_16x16x32_bf16 v[118:121], v[174:177], v[190:193], v[118:121]
	v_mfma_f32_16x16x32_bf16 v[114:117], v[182:185], v[190:193], v[114:117]
	v_mfma_f32_16x16x32_bf16 v[102:105], v[174:177], v[198:201], v[102:105]
	v_mfma_f32_16x16x32_bf16 v[98:101], v[182:185], v[198:201], v[98:101]
	v_mfma_f32_16x16x32_bf16 v[86:89], v[174:177], v[206:209], v[86:89]
	v_mfma_f32_16x16x32_bf16 v[82:85], v[182:185], v[206:209], v[82:85]
	v_mfma_f32_16x16x32_bf16 v[70:73], v[174:177], v[214:217], v[70:73]
	v_mfma_f32_16x16x32_bf16 v[66:69], v[182:185], v[214:217], v[66:69]
	v_mfma_f32_16x16x32_bf16 v[118:121], v[178:181], v[194:197], v[118:121]
	v_mfma_f32_16x16x32_bf16 v[114:117], v[186:189], v[194:197], v[114:117]
	v_mfma_f32_16x16x32_bf16 v[102:105], v[178:181], v[202:205], v[102:105]
	v_mfma_f32_16x16x32_bf16 v[98:101], v[186:189], v[202:205], v[98:101]
	v_mfma_f32_16x16x32_bf16 v[86:89], v[178:181], v[210:213], v[86:89]
	v_mfma_f32_16x16x32_bf16 v[82:85], v[186:189], v[210:213], v[82:85]
	v_mfma_f32_16x16x32_bf16 v[70:73], v[178:181], v[218:221], v[70:73]
	v_mfma_f32_16x16x32_bf16 v[66:69], v[186:189], v[218:221], v[66:69]
	s_setprio 0
	s_barrier
	s_add_i32 s12, s64, s52
	v_lshl_add_u64 v[144:145], s[44:45], 0, v[0:1]
	s_mov_b32 m0, s12
	ds_read_b128 v[190:193], v149 offset:16384
	ds_read_b128 v[194:197], v149 offset:17408
	ds_read_b128 v[198:201], v149 offset:18432
	ds_read_b128 v[202:205], v149 offset:19456
	ds_read_b128 v[206:209], v149 offset:20480
	ds_read_b128 v[210:213], v149 offset:21504
	ds_read_b128 v[214:217], v149 offset:22528
	ds_read_b128 v[218:221], v149 offset:23552
	global_load_lds_dwordx4 v[144:145], off
	s_add_i32 m0, s12, 0x2000
	s_add_u32 s12, s44, 0x56000
	v_lshl_add_u64 v[222:223], s[44:45], 0, v[134:135]
	s_addc_u32 s13, s45, 0
	s_add_i32 s64, s65, s52
	global_load_lds_dwordx4 v[222:223], off
	v_lshl_add_u64 v[224:225], s[12:13], 0, v[0:1]
	s_mov_b32 m0, s64
	v_lshl_add_u64 v[226:227], s[46:47], 0, v[132:133]
	global_load_lds_dwordx4 v[224:225], off
	v_lshl_add_u64 v[224:225], s[12:13], 0, v[134:135]
	s_add_i32 m0, s64, 0x2000
	s_nop 0
	global_load_lds_dwordx4 v[224:225], off
	v_lshl_add_u64 v[224:225], s[46:47], 0, v[130:131]
	s_mov_b32 m0, s53
	s_nop 0
	global_load_lds_dwordx4 v[224:225], off
	s_mov_b32 m0, s54
	s_nop 0
	global_load_lds_dwordx4 v[226:227], off
	s_waitcnt vmcnt(8)
	s_waitcnt lgkmcnt(0)
	s_barrier
; #define PG8_STAGE(bufoff, gbase, voff) do { _Pragma("unroll") for (int _i = 0; _i < 2; ++_i) \
;         __builtin_amdgcn_global_load_lds((const __attribute__((address_space(1))) unsigned*)((const char*)(gbase) + (voff)[_i]), (LAS unsigned*)(lds + (bufoff) + ldsw + _i * 8192), 16, 0, 0); } while (0)
; #define PG8_LDA(dst, b, h) do { _Pragma("unroll") for (int m = 0; m < 4; ++m) _Pragma("unroll") for (int k = 0; k < 2; ++k) dst[m][k] = *(const LAS bf16x8*)(lds + PG8_SA(b, h) + aoff + m * 2048 + k * 1024); } while (0)
; #define PG8_LDB(dst, b, h) do { _Pragma("unroll") for (int n = 0; n < 2; ++n) _Pragma("unroll") for (int k = 0; k < 2; ++k) dst[n][k] = *(const LAS bf16x8*)(lds + PG8_SB(b, h) + boff + n * 2048 + k * 1024); } while (0)
; #define PG8_MMA(ai, bj, At, Bt) do { __builtin_amdgcn_s_setprio(1); _Pragma("unroll") for (int m = 0; m < 4; ++m) _Pragma("unroll") for (int n = 0; n < 2; ++n) _Pragma("unroll") for (int k = 0; k < 2; ++k) \
;         acc[ai][bj][m][n] = __builtin_amdgcn_mfma_f32_16x16x32_bf16(Bt[n][k], At[m][k], acc[ai][bj][m][n], 0, 0, 0); __builtin_amdgcn_s_setprio(0); } while (0)
; #define PG8_WAIT_V(n) asm volatile("s_waitcnt vmcnt(" #n ")" ::: "memory")
; #define PG8_WAIT_L(n) asm volatile("s_waitcnt lgkmcnt(" #n ")" ::: "memory")
; #define PG8_BAR __builtin_amdgcn_s_barrier()
; #define PG8_SCHED __builtin_amdgcn_sched_barrier(0)
; template <class Epi, class SchedT, bool ALIGN_EPI, bool SP2>
; __device__ __forceinline__ void gemm_phase(LAS unsigned char* lds, const int ldk, const int nt, const SchedT& S, const Epi& E) {
;     ...
;             PG8_WAIT_V(8); PG8_WAIT_L(0); PG8_BAR; PG8_MMA(0, 0, At, B0); PG8_MMA(0, 1, At, B1); PG8_BAR; PG8_SCHED;
;             PG8_LDA(At, 0, 1); PG8_STAGE(PG8_SB(0, 0), b2, voffB); PG8_STAGE(PG8_SB(0, 1), b2 + hstepB, voffB); PG8_STAGE(PG8_SA(0, 0), a2, voffA);
;             PG8_WAIT_V(8); PG8_WAIT_L(0); PG8_BAR; PG8_MMA(1, 0, At, B0); PG8_MMA(1, 1, At, B1); PG8_BAR; PG8_SCHED;
;             PG8_LDB(B0, 1, 0); PG8_LDB(B1, 1, 1); PG8_SCHED; PG8_LDA(At, 1, 0); PG8_STAGE(PG8_SA(0, 1), a2 + hstep, voffA);
;             PG8_WAIT_V(8); PG8_WAIT_L(0); PG8_BAR; PG8_MMA(0, 0, At, B0); PG8_MMA(0, 1, At, B1); PG8_BAR; PG8_SCHED;
	s_setprio 1
	s_waitcnt lgkmcnt(0)
	v_mfma_f32_16x16x32_bf16 v[62:65], v[140:143], v[190:193], v[62:65]
	v_mfma_f32_16x16x32_bf16 v[58:61], v[154:157], v[190:193], v[58:61]
	v_mfma_f32_16x16x32_bf16 v[46:49], v[140:143], v[198:201], v[46:49]
	v_mfma_f32_16x16x32_bf16 v[42:45], v[154:157], v[198:201], v[42:45]
	v_mfma_f32_16x16x32_bf16 v[30:33], v[140:143], v[206:209], v[30:33]
	v_mfma_f32_16x16x32_bf16 v[26:29], v[154:157], v[206:209], v[26:29]
	v_mfma_f32_16x16x32_bf16 v[14:17], v[140:143], v[214:217], v[14:17]
	v_mfma_f32_16x16x32_bf16 v[10:13], v[154:157], v[214:217], v[10:13]
	v_mfma_f32_16x16x32_bf16 v[62:65], v[150:153], v[194:197], v[62:65]
	v_mfma_f32_16x16x32_bf16 v[58:61], v[158:161], v[194:197], v[58:61]
	v_mfma_f32_16x16x32_bf16 v[46:49], v[150:153], v[202:205], v[46:49]
	v_mfma_f32_16x16x32_bf16 v[42:45], v[158:161], v[202:205], v[42:45]
	v_mfma_f32_16x16x32_bf16 v[30:33], v[150:153], v[210:213], v[30:33]
	v_mfma_f32_16x16x32_bf16 v[26:29], v[158:161], v[210:213], v[26:29]
	v_mfma_f32_16x16x32_bf16 v[14:17], v[150:153], v[218:221], v[14:17]
	v_mfma_f32_16x16x32_bf16 v[10:13], v[158:161], v[218:221], v[10:13]
	s_setprio 0
	s_setprio 1
	v_mfma_f32_16x16x32_bf16 v[54:57], v[174:177], v[190:193], v[54:57]
	v_mfma_f32_16x16x32_bf16 v[50:53], v[182:185], v[190:193], v[50:53]
	v_mfma_f32_16x16x32_bf16 v[38:41], v[174:177], v[198:201], v[38:41]
	v_mfma_f32_16x16x32_bf16 v[34:37], v[182:185], v[198:201], v[34:37]
	v_mfma_f32_16x16x32_bf16 v[22:25], v[174:177], v[206:209], v[22:25]
	v_mfma_f32_16x16x32_bf16 v[18:21], v[182:185], v[206:209], v[18:21]
	v_mfma_f32_16x16x32_bf16 v[6:9], v[174:177], v[214:217], v[6:9]
	v_mfma_f32_16x16x32_bf16 v[2:5], v[182:185], v[214:217], v[2:5]
	v_mfma_f32_16x16x32_bf16 v[54:57], v[178:181], v[194:197], v[54:57]
	v_mfma_f32_16x16x32_bf16 v[50:53], v[186:189], v[194:197], v[50:53]
	v_mfma_f32_16x16x32_bf16 v[38:41], v[178:181], v[202:205], v[38:41]
	v_mfma_f32_16x16x32_bf16 v[34:37], v[186:189], v[202:205], v[34:37]
	v_mfma_f32_16x16x32_bf16 v[22:25], v[178:181], v[210:213], v[22:25]
	v_mfma_f32_16x16x32_bf16 v[18:21], v[186:189], v[210:213], v[18:21]
	v_mfma_f32_16x16x32_bf16 v[6:9], v[178:181], v[218:221], v[6:9]
	v_mfma_f32_16x16x32_bf16 v[2:5], v[186:189], v[218:221], v[2:5]
	s_setprio 0
	s_barrier
	s_add_i32 s64, 0, 0x18000
	s_add_i32 s65, 0, 0x1c000
	v_add_u32_e32 v158, s64, v147
	v_add_u32_e32 v186, s65, v147
	ds_read_b128 v[140:143], v158
	ds_read_b128 v[150:153], v158 offset:1024
	ds_read_b128 v[154:157], v158 offset:2048
	ds_read_b128 v[158:161], v158 offset:3072
	ds_read_b128 v[174:177], v186
	ds_read_b128 v[178:181], v186 offset:1024
	ds_read_b128 v[182:185], v186 offset:2048
	ds_read_b128 v[186:189], v186 offset:3072
	s_add_u32 s12, s46, 0x158000
	s_addc_u32 s13, s47, 0
	s_mov_b32 m0, s55
	v_lshl_add_u64 v[228:229], s[12:13], 0, v[130:131]
	ds_read_b128 v[190:193], v149 offset:32768
	ds_read_b128 v[194:197], v149 offset:33792
	ds_read_b128 v[198:201], v149 offset:34816
	ds_read_b128 v[202:205], v149 offset:35840
	ds_read_b128 v[206:209], v149 offset:36864
	ds_read_b128 v[210:213], v149 offset:37888
	ds_read_b128 v[214:217], v149 offset:38912
	ds_read_b128 v[218:221], v149 offset:39936
	global_load_lds_dwordx4 v[228:229], off
	v_lshl_add_u64 v[228:229], s[12:13], 0, v[132:133]
	s_mov_b32 m0, s56
	s_nop 0
	global_load_lds_dwordx4 v[228:229], off
	s_waitcnt vmcnt(8)
	s_waitcnt lgkmcnt(0)
	s_barrier
	s_setprio 1
	s_waitcnt lgkmcnt(0)
	v_mfma_f32_16x16x32_bf16 v[126:129], v[140:143], v[190:193], v[126:129]
	v_mfma_f32_16x16x32_bf16 v[122:125], v[154:157], v[190:193], v[122:125]
	v_mfma_f32_16x16x32_bf16 v[110:113], v[140:143], v[198:201], v[110:113]
	v_mfma_f32_16x16x32_bf16 v[106:109], v[154:157], v[198:201], v[106:109]
	v_mfma_f32_16x16x32_bf16 v[94:97], v[140:143], v[206:209], v[94:97]
	v_mfma_f32_16x16x32_bf16 v[90:93], v[154:157], v[206:209], v[90:93]
	v_mfma_f32_16x16x32_bf16 v[78:81], v[140:143], v[214:217], v[78:81]
	v_mfma_f32_16x16x32_bf16 v[74:77], v[154:157], v[214:217], v[74:77]
	v_mfma_f32_16x16x32_bf16 v[126:129], v[150:153], v[194:197], v[126:129]
	v_mfma_f32_16x16x32_bf16 v[122:125], v[158:161], v[194:197], v[122:125]
	v_mfma_f32_16x16x32_bf16 v[110:113], v[150:153], v[202:205], v[110:113]
	v_mfma_f32_16x16x32_bf16 v[106:109], v[158:161], v[202:205], v[106:109]
	v_mfma_f32_16x16x32_bf16 v[94:97], v[150:153], v[210:213], v[94:97]
	v_mfma_f32_16x16x32_bf16 v[90:93], v[158:161], v[210:213], v[90:93]
	v_mfma_f32_16x16x32_bf16 v[78:81], v[150:153], v[218:221], v[78:81]
	v_mfma_f32_16x16x32_bf16 v[74:77], v[158:161], v[218:221], v[74:77]
	s_setprio 0
	s_setprio 1
	v_mfma_f32_16x16x32_bf16 v[118:121], v[174:177], v[190:193], v[118:121]
	v_mfma_f32_16x16x32_bf16 v[114:117], v[182:185], v[190:193], v[114:117]
	v_mfma_f32_16x16x32_bf16 v[102:105], v[174:177], v[198:201], v[102:105]
	v_mfma_f32_16x16x32_bf16 v[98:101], v[182:185], v[198:201], v[98:101]
	v_mfma_f32_16x16x32_bf16 v[86:89], v[174:177], v[206:209], v[86:89]
	v_mfma_f32_16x16x32_bf16 v[82:85], v[182:185], v[206:209], v[82:85]
	v_mfma_f32_16x16x32_bf16 v[70:73], v[174:177], v[214:217], v[70:73]
	v_mfma_f32_16x16x32_bf16 v[66:69], v[182:185], v[214:217], v[66:69]
	v_mfma_f32_16x16x32_bf16 v[118:121], v[178:181], v[194:197], v[118:121]
	v_mfma_f32_16x16x32_bf16 v[114:117], v[186:189], v[194:197], v[114:117]
	v_mfma_f32_16x16x32_bf16 v[102:105], v[178:181], v[202:205], v[102:105]
	v_mfma_f32_16x16x32_bf16 v[98:101], v[186:189], v[202:205], v[98:101]
	v_mfma_f32_16x16x32_bf16 v[86:89], v[178:181], v[210:213], v[86:89]
	v_mfma_f32_16x16x32_bf16 v[82:85], v[186:189], v[210:213], v[82:85]
	v_mfma_f32_16x16x32_bf16 v[70:73], v[178:181], v[218:221], v[70:73]
	v_mfma_f32_16x16x32_bf16 v[66:69], v[186:189], v[218:221], v[66:69]
	s_setprio 0
	s_barrier
; #define PG8_STAGE(bufoff, gbase, voff) do { _Pragma("unroll") for (int _i = 0; _i < 2; ++_i) \
;         __builtin_amdgcn_global_load_lds((const __attribute__((address_space(1))) unsigned*)((const char*)(gbase) + (voff)[_i]), (LAS unsigned*)(lds + (bufoff) + ldsw + _i * 8192), 16, 0, 0); } while (0)
; #define PG8_LDA(dst, b, h) do { _Pragma("unroll") for (int m = 0; m < 4; ++m) _Pragma("unroll") for (int k = 0; k < 2; ++k) dst[m][k] = *(const LAS bf16x8*)(lds + PG8_SA(b, h) + aoff + m * 2048 + k * 1024); } while (0)
; #define PG8_MMA(ai, bj, At, Bt) do { __builtin_amdgcn_s_setprio(1); _Pragma("unroll") for (int m = 0; m < 4; ++m) _Pragma("unroll") for (int n = 0; n < 2; ++n) _Pragma("unroll") for (int k = 0; k < 2; ++k) \
;         acc[ai][bj][m][n] = __builtin_amdgcn_mfma_f32_16x16x32_bf16(Bt[n][k], At[m][k], acc[ai][bj][m][n], 0, 0, 0); __builtin_amdgcn_s_setprio(0); } while (0)
; #define PG8_WAIT_V(n) asm volatile("s_waitcnt vmcnt(" #n ")" ::: "memory")
; #define PG8_WAIT_L(n) asm volatile("s_waitcnt lgkmcnt(" #n ")" ::: "memory")
; #define PG8_BAR __builtin_amdgcn_s_barrier()
; #define PG8_SCHED __builtin_amdgcn_sched_barrier(0)
; template <class Epi, class SchedT, bool ALIGN_EPI, bool SP2>
; __device__ __forceinline__ void gemm_phase(LAS unsigned char* lds, const int ldk, const int nt, const SchedT& S, const Epi& E) {
;     ...
;             PG8_LDA(At, 1, 1); PG8_STAGE(PG8_SB(1, 0), b3, voffB); PG8_STAGE(PG8_SB(1, 1), b3 + hstepB, voffB); PG8_STAGE(PG8_SA(1, 0), a3, voffA);
;             PG8_WAIT_V(8); PG8_WAIT_L(0); PG8_BAR; PG8_MMA(1, 0, At, B0); PG8_MMA(1, 1, At, B1); PG8_BAR; PG8_SCHED;
;     __device__ __forceinline__ void operator()(f32x4 (&acc)[2][2][4][2], const Unit& u, int wr, int wc, int fr, int fq) const {
;         const int row0 = u.pm * BM + wr * 64 + fr, col0 = u.pn * BM + wc * 64 + 8 * fq;
; #pragma unroll
;         for (int ai = 0; ai < 2; ++ai)
; #pragma unroll
;             for (int m = 0; m < 4; ++m) {
;                 const int row = row0 + ai * HALF + m * 16; float sq = 0.f;
; #pragma unroll
;                 for (int bj = 0; bj < 2; ++bj) {
;                     const size_t off = (size_t)row * D + col0 + bj * 32;
;                     const u32x4 xw = *(const u32x4*)(xin + off);
	s_add_i32 s12, s64, s52
	v_lshl_add_u64 v[144:145], v[144:145], 0, s[24:25]
	s_mov_b32 m0, s12
	ds_read_b128 v[190:193], v149 offset:49152
	ds_read_b128 v[194:197], v149 offset:50176
	ds_read_b128 v[198:201], v149 offset:51200
	ds_read_b128 v[202:205], v149 offset:52224
	ds_read_b128 v[206:209], v149 offset:53248
	ds_read_b128 v[210:213], v149 offset:54272
	ds_read_b128 v[214:217], v149 offset:55296
	ds_read_b128 v[218:221], v149 offset:56320
	global_load_lds_dwordx4 v[144:145], off
	s_add_i32 m0, s12, 0x2000
	s_add_u32 s12, s44, 0x56080
	v_lshl_add_u64 v[144:145], v[222:223], 0, s[24:25]
	s_addc_u32 s13, s45, 0
	s_add_i32 s44, s65, s52
	global_load_lds_dwordx4 v[144:145], off
	v_lshl_add_u64 v[144:145], s[12:13], 0, v[0:1]
	s_mov_b32 m0, s44
	s_nop 0
	global_load_lds_dwordx4 v[144:145], off
	v_lshl_add_u64 v[144:145], s[12:13], 0, v[134:135]
	s_add_i32 m0, s44, 0x2000
	s_nop 0
	global_load_lds_dwordx4 v[144:145], off
	v_lshl_add_u64 v[144:145], v[224:225], 0, s[24:25]
	s_mov_b32 m0, s58
	s_nop 0
	global_load_lds_dwordx4 v[144:145], off
	v_lshl_add_u64 v[144:145], v[226:227], 0, s[24:25]
	s_mov_b32 m0, s59
	s_nop 0
	global_load_lds_dwordx4 v[144:145], off
	s_waitcnt vmcnt(8)
	s_waitcnt lgkmcnt(0)
	s_barrier
	s_setprio 1
	s_waitcnt lgkmcnt(0)
	v_mfma_f32_16x16x32_bf16 v[62:65], v[140:143], v[190:193], v[62:65]
	v_mfma_f32_16x16x32_bf16 v[58:61], v[154:157], v[190:193], v[58:61]
	v_mfma_f32_16x16x32_bf16 v[46:49], v[140:143], v[198:201], v[46:49]
	v_mfma_f32_16x16x32_bf16 v[42:45], v[154:157], v[198:201], v[42:45]
	v_mfma_f32_16x16x32_bf16 v[30:33], v[140:143], v[206:209], v[30:33]
	v_mfma_f32_16x16x32_bf16 v[26:29], v[154:157], v[206:209], v[26:29]
	v_mfma_f32_16x16x32_bf16 v[14:17], v[140:143], v[214:217], v[14:17]
	v_mfma_f32_16x16x32_bf16 v[10:13], v[154:157], v[214:217], v[10:13]
	v_mfma_f32_16x16x32_bf16 v[62:65], v[150:153], v[194:197], v[62:65]
	v_mfma_f32_16x16x32_bf16 v[58:61], v[158:161], v[194:197], v[58:61]
	v_mfma_f32_16x16x32_bf16 v[46:49], v[150:153], v[202:205], v[46:49]
	v_mfma_f32_16x16x32_bf16 v[42:45], v[158:161], v[202:205], v[42:45]
	v_mfma_f32_16x16x32_bf16 v[30:33], v[150:153], v[210:213], v[30:33]
	v_mfma_f32_16x16x32_bf16 v[26:29], v[158:161], v[210:213], v[26:29]
	v_mfma_f32_16x16x32_bf16 v[14:17], v[150:153], v[218:221], v[14:17]
	v_mfma_f32_16x16x32_bf16 v[10:13], v[158:161], v[218:221], v[10:13]
	s_setprio 0
	s_setprio 1
	v_mfma_f32_16x16x32_bf16 v[54:57], v[174:177], v[190:193], v[54:57]
	v_mfma_f32_16x16x32_bf16 v[50:53], v[182:185], v[190:193], v[50:53]
	v_mfma_f32_16x16x32_bf16 v[38:41], v[174:177], v[198:201], v[38:41]
	v_mfma_f32_16x16x32_bf16 v[34:37], v[182:185], v[198:201], v[34:37]
	v_mfma_f32_16x16x32_bf16 v[22:25], v[174:177], v[206:209], v[22:25]
	v_mfma_f32_16x16x32_bf16 v[18:21], v[182:185], v[206:209], v[18:21]
	v_mfma_f32_16x16x32_bf16 v[6:9], v[174:177], v[214:217], v[6:9]
	v_mfma_f32_16x16x32_bf16 v[2:5], v[182:185], v[214:217], v[2:5]
	v_mfma_f32_16x16x32_bf16 v[54:57], v[178:181], v[194:197], v[54:57]
	v_mfma_f32_16x16x32_bf16 v[50:53], v[186:189], v[194:197], v[50:53]
	v_mfma_f32_16x16x32_bf16 v[38:41], v[178:181], v[202:205], v[38:41]
	v_mfma_f32_16x16x32_bf16 v[34:37], v[186:189], v[202:205], v[34:37]
	v_mfma_f32_16x16x32_bf16 v[22:25], v[178:181], v[210:213], v[22:25]
	v_mfma_f32_16x16x32_bf16 v[18:21], v[186:189], v[210:213], v[18:21]
	v_mfma_f32_16x16x32_bf16 v[6:9], v[178:181], v[218:221], v[6:9]
	v_mfma_f32_16x16x32_bf16 v[2:5], v[186:189], v[218:221], v[2:5]
	s_setprio 0
	s_barrier
	s_add_i32 s83, s83, 2
	s_add_u32 s81, s81, 0x100
	s_addc_u32 s82, s82, 0
	s_cmpk_gt_u32 s83, 0x53
	s_mov_b64 s[12:13], s[16:17]
	s_cbranch_scc0 .LBB0_948
	v_lshl_add_u32 v142, s63, 8, v146
	v_lshl_or_b32 v140, s22, 8, v148
	v_lshlrev_b32_e32 v141, 12, v142
	v_lshl_add_u32 v150, v140, 1, v141
	v_add_u32_e32 v151, 0x10000, v150
	v_add_u32_e32 v152, 0x20000, v150
	v_add_u32_e32 v153, 0x30000, v150
	v_add_u32_e32 v154, 0x80000, v150
	v_add_u32_e32 v155, 0x90000, v150
	v_add_u32_e32 v156, 0xa0000, v150
	v_add_u32_e32 v157, 0xb0000, v150
	global_load_dwordx4 v[174:177], v150, s[20:21]
	global_load_dwordx4 v[178:181], v150, s[20:21] offset:64
	global_load_dwordx4 v[182:185], v151, s[20:21]
	global_load_dwordx4 v[186:189], v151, s[20:21] offset:64
	global_load_dwordx4 v[190:193], v152, s[20:21]
	global_load_dwordx4 v[194:197], v152, s[20:21] offset:64
	global_load_dwordx4 v[198:201], v153, s[20:21]
	global_load_dwordx4 v[202:205], v153, s[20:21] offset:64
	global_load_dwordx4 v[206:209], v154, s[20:21]
	global_load_dwordx4 v[210:213], v154, s[20:21] offset:64
	global_load_dwordx4 v[214:217], v155, s[20:21]
	global_load_dwordx4 v[218:221], v155, s[20:21] offset:64
	global_load_dwordx4 v[222:225], v156, s[20:21]
	global_load_dwordx4 v[226:229], v156, s[20:21] offset:64
	global_load_dwordx4 v[230:233], v157, s[20:21]
	global_load_dwordx4 v[234:237], v157, s[20:21] offset:64
	s_lshl_b32 s44, s22, 4
	s_lshl_b32 s45, s57, 2
	s_add_i32 s44, s44, s45
	v_lshl_add_u32 v158, v142, 7, s44
	v_add_u32_e32 v159, 0x1000, v158
	v_add_u32_e32 v160, 0x4000, v158
	v_add_u32_e32 v161, 0x5000, v158
	v_xor_b32_e32 v239, 16, v241
	v_xor_b32_e32 v252, 32, v241
	v_lshlrev_b32_e32 v239, 2, v239
	v_lshlrev_b32_e32 v252, 2, v252
	s_and_b64 vcc, exec, s[40:41]
	s_cbranch_vccz .LBB0_951
	s_barrier
; __device__ __forceinline__ float bf_lo(unsigned w) { return __uint_as_float(w << 16); }
; __device__ __forceinline__ float bf_hi(unsigned w) { return __uint_as_float(w & 0xffff0000u); }
; __device__ __forceinline__ u32x4 pack8(f32x4 a, f32x4 b) { u32x4 w; w.x = cvt_pk_bf16(a[0], a[1]); w.y = cvt_pk_bf16(a[2], a[3]); w.z = cvt_pk_bf16(b[0], b[1]); w.w = cvt_pk_bf16(b[2], b[3]); return w; }
;     __device__ __forceinline__ void operator()(f32x4 (&acc)[2][2][4][2], const Unit& u, int wr, int wc, int fr, int fq) const {
;     ...
;         for (int ai = 0; ai < 2; ++ai)
; #pragma unroll
;             for (int m = 0; m < 4; ++m) {
;                 const int row = row0 + ai * HALF + m * 16; float sq = 0.f;
; #pragma unroll
;                 for (int bj = 0; bj < 2; ++bj) {
;                     const size_t off = (size_t)row * D + col0 + bj * 32;
;                     const u32x4 xw = *(const u32x4*)(xin + off);
;                     const f32x4 v0 = acc[ai][bj][m][0] + (f32x4){bf_lo(xw.x), bf_hi(xw.x), bf_lo(xw.y), bf_hi(xw.y)}, v1 = acc[ai][bj][m][1] + (f32x4){bf_lo(xw.z), bf_hi(xw.z), bf_lo(xw.w), bf_hi(xw.w)};
;                     *(u32x4*)(xb + off) = pack8(v0, v1);
;                     sq += (v0[0] * v0[0] + v0[1] * v0[1]) + (v0[2] * v0[2] + v0[3] * v0[3]) + (v1[0] * v1[0] + v1[1] * v1[1]) + (v1[2] * v1[2] + v1[3] * v1[3]);
;                 }
.LBB0_951:
	s_waitcnt vmcnt(15)
	v_lshlrev_b32_e32 v246, 16, v174
	v_and_b32_e32 v247, 0xffff0000, v174
	v_lshlrev_b32_e32 v248, 16, v175
	v_and_b32_e32 v249, 0xffff0000, v175
	v_pk_add_f32 v[126:127], v[126:127], v[246:247]
	v_pk_add_f32 v[128:129], v[128:129], v[248:249]
	v_lshlrev_b32_e32 v246, 16, v176
	v_and_b32_e32 v247, 0xffff0000, v176
	v_lshlrev_b32_e32 v248, 16, v177
	v_and_b32_e32 v249, 0xffff0000, v177
	v_pk_add_f32 v[122:123], v[122:123], v[246:247]
	v_pk_add_f32 v[124:125], v[124:125], v[248:249]
	v_cvt_pk_bf16_f32 v174, v126, v127
	v_cvt_pk_bf16_f32 v175, v128, v129
	v_cvt_pk_bf16_f32 v176, v122, v123
	v_cvt_pk_bf16_f32 v177, v124, v125
	global_store_dwordx4 v150, v[174:177], s[30:31]
	v_pk_mul_f32 v[250:251], v[126:127], v[126:127]
	v_pk_fma_f32 v[250:251], v[128:129], v[128:129], v[250:251]
	v_pk_fma_f32 v[250:251], v[122:123], v[122:123], v[250:251]
	v_pk_fma_f32 v[250:251], v[124:125], v[124:125], v[250:251]
	s_waitcnt vmcnt(15)
	v_lshlrev_b32_e32 v246, 16, v178
	v_and_b32_e32 v247, 0xffff0000, v178
	v_lshlrev_b32_e32 v248, 16, v179
	v_and_b32_e32 v249, 0xffff0000, v179
	v_pk_add_f32 v[118:119], v[118:119], v[246:247]
	v_pk_add_f32 v[120:121], v[120:121], v[248:249]
	v_lshlrev_b32_e32 v246, 16, v180
	v_and_b32_e32 v247, 0xffff0000, v180
	v_lshlrev_b32_e32 v248, 16, v181
	v_and_b32_e32 v249, 0xffff0000, v181
	v_pk_add_f32 v[114:115], v[114:115], v[246:247]
	v_pk_add_f32 v[116:117], v[116:117], v[248:249]
	v_cvt_pk_bf16_f32 v178, v118, v119
	v_cvt_pk_bf16_f32 v179, v120, v121
	v_cvt_pk_bf16_f32 v180, v114, v115
	v_cvt_pk_bf16_f32 v181, v116, v117
	global_store_dwordx4 v150, v[178:181], s[30:31] offset:64
	v_pk_fma_f32 v[250:251], v[118:119], v[118:119], v[250:251]
	v_pk_fma_f32 v[250:251], v[120:121], v[120:121], v[250:251]
	v_pk_fma_f32 v[250:251], v[114:115], v[114:115], v[250:251]
	v_pk_fma_f32 v[250:251], v[116:117], v[116:117], v[250:251]
	v_add_f32_e32 v140, v250, v251
	s_waitcnt vmcnt(15)
	v_lshlrev_b32_e32 v246, 16, v182
	v_and_b32_e32 v247, 0xffff0000, v182
	v_lshlrev_b32_e32 v248, 16, v183
	v_and_b32_e32 v249, 0xffff0000, v183
	v_pk_add_f32 v[110:111], v[110:111], v[246:247]
	v_pk_add_f32 v[112:113], v[112:113], v[248:249]
	v_lshlrev_b32_e32 v246, 16, v184
	v_and_b32_e32 v247, 0xffff0000, v184
	v_lshlrev_b32_e32 v248, 16, v185
	v_and_b32_e32 v249, 0xffff0000, v185
	v_pk_add_f32 v[106:107], v[106:107], v[246:247]
	v_pk_add_f32 v[108:109], v[108:109], v[248:249]
	v_cvt_pk_bf16_f32 v182, v110, v111
	v_cvt_pk_bf16_f32 v183, v112, v113
	v_cvt_pk_bf16_f32 v184, v106, v107
	v_cvt_pk_bf16_f32 v185, v108, v109
	global_store_dwordx4 v151, v[182:185], s[30:31]
	v_pk_mul_f32 v[250:251], v[110:111], v[110:111]
	v_pk_fma_f32 v[250:251], v[112:113], v[112:113], v[250:251]
	v_pk_fma_f32 v[250:251], v[106:107], v[106:107], v[250:251]
	v_pk_fma_f32 v[250:251], v[108:109], v[108:109], v[250:251]
	s_waitcnt vmcnt(15)
	v_lshlrev_b32_e32 v246, 16, v186
	v_and_b32_e32 v247, 0xffff0000, v186
	v_lshlrev_b32_e32 v248, 16, v187
	v_and_b32_e32 v249, 0xffff0000, v187
	v_pk_add_f32 v[102:103], v[102:103], v[246:247]
	v_pk_add_f32 v[104:105], v[104:105], v[248:249]
	v_lshlrev_b32_e32 v246, 16, v188
	v_and_b32_e32 v247, 0xffff0000, v188
	v_lshlrev_b32_e32 v248, 16, v189
	v_and_b32_e32 v249, 0xffff0000, v189
	v_pk_add_f32 v[98:99], v[98:99], v[246:247]
	v_pk_add_f32 v[100:101], v[100:101], v[248:249]
	v_cvt_pk_bf16_f32 v186, v102, v103
	v_cvt_pk_bf16_f32 v187, v104, v105
	v_cvt_pk_bf16_f32 v188, v98, v99
	v_cvt_pk_bf16_f32 v189, v100, v101
	global_store_dwordx4 v151, v[186:189], s[30:31] offset:64
	v_pk_fma_f32 v[250:251], v[102:103], v[102:103], v[250:251]
	v_pk_fma_f32 v[250:251], v[104:105], v[104:105], v[250:251]
	v_pk_fma_f32 v[250:251], v[98:99], v[98:99], v[250:251]
	v_pk_fma_f32 v[250:251], v[100:101], v[100:101], v[250:251]
	v_add_f32_e32 v141, v250, v251
	s_waitcnt vmcnt(15)
	v_lshlrev_b32_e32 v246, 16, v190
	v_and_b32_e32 v247, 0xffff0000, v190
	v_lshlrev_b32_e32 v248, 16, v191
	v_and_b32_e32 v249, 0xffff0000, v191
	v_pk_add_f32 v[94:95], v[94:95], v[246:247]
	v_pk_add_f32 v[96:97], v[96:97], v[248:249]
	v_lshlrev_b32_e32 v246, 16, v192
	v_and_b32_e32 v247, 0xffff0000, v192
	v_lshlrev_b32_e32 v248, 16, v193
	v_and_b32_e32 v249, 0xffff0000, v193
	v_pk_add_f32 v[90:91], v[90:91], v[246:247]
	v_pk_add_f32 v[92:93], v[92:93], v[248:249]
	v_cvt_pk_bf16_f32 v190, v94, v95
	v_cvt_pk_bf16_f32 v191, v96, v97
	v_cvt_pk_bf16_f32 v192, v90, v91
	v_cvt_pk_bf16_f32 v193, v92, v93
	global_store_dwordx4 v152, v[190:193], s[30:31]
	v_pk_mul_f32 v[250:251], v[94:95], v[94:95]
	v_pk_fma_f32 v[250:251], v[96:97], v[96:97], v[250:251]
	v_pk_fma_f32 v[250:251], v[90:91], v[90:91], v[250:251]
	v_pk_fma_f32 v[250:251], v[92:93], v[92:93], v[250:251]
	s_waitcnt vmcnt(15)
	v_lshlrev_b32_e32 v246, 16, v194
	v_and_b32_e32 v247, 0xffff0000, v194
	v_lshlrev_b32_e32 v248, 16, v195
	v_and_b32_e32 v249, 0xffff0000, v195
	v_pk_add_f32 v[86:87], v[86:87], v[246:247]
	v_pk_add_f32 v[88:89], v[88:89], v[248:249]
	v_lshlrev_b32_e32 v246, 16, v196
	v_and_b32_e32 v247, 0xffff0000, v196
	v_lshlrev_b32_e32 v248, 16, v197
	v_and_b32_e32 v249, 0xffff0000, v197
	v_pk_add_f32 v[82:83], v[82:83], v[246:247]
	v_pk_add_f32 v[84:85], v[84:85], v[248:249]
	v_cvt_pk_bf16_f32 v194, v86, v87
	v_cvt_pk_bf16_f32 v195, v88, v89
	v_cvt_pk_bf16_f32 v196, v82, v83
	v_cvt_pk_bf16_f32 v197, v84, v85
	global_store_dwordx4 v152, v[194:197], s[30:31] offset:64
	v_pk_fma_f32 v[250:251], v[86:87], v[86:87], v[250:251]
	v_pk_fma_f32 v[250:251], v[88:89], v[88:89], v[250:251]
	v_pk_fma_f32 v[250:251], v[82:83], v[82:83], v[250:251]
	v_pk_fma_f32 v[250:251], v[84:85], v[84:85], v[250:251]
	v_add_f32_e32 v142, v250, v251
	s_waitcnt vmcnt(15)
; __device__ __forceinline__ float bf_lo(unsigned w) { return __uint_as_float(w << 16); }
; __device__ __forceinline__ float bf_hi(unsigned w) { return __uint_as_float(w & 0xffff0000u); }
; __device__ __forceinline__ u32x4 pack8(f32x4 a, f32x4 b) { u32x4 w; w.x = cvt_pk_bf16(a[0], a[1]); w.y = cvt_pk_bf16(a[2], a[3]); w.z = cvt_pk_bf16(b[0], b[1]); w.w = cvt_pk_bf16(b[2], b[3]); return w; }
;     __device__ __forceinline__ void operator()(f32x4 (&acc)[2][2][4][2], const Unit& u, int wr, int wc, int fr, int fq) const {
;     ...
;         for (int ai = 0; ai < 2; ++ai)
; #pragma unroll
;             for (int m = 0; m < 4; ++m) {
;                 const int row = row0 + ai * HALF + m * 16; float sq = 0.f;
; #pragma unroll
;                 for (int bj = 0; bj < 2; ++bj) {
;                     const size_t off = (size_t)row * D + col0 + bj * 32;
;                     const u32x4 xw = *(const u32x4*)(xin + off);
;                     const f32x4 v0 = acc[ai][bj][m][0] + (f32x4){bf_lo(xw.x), bf_hi(xw.x), bf_lo(xw.y), bf_hi(xw.y)}, v1 = acc[ai][bj][m][1] + (f32x4){bf_lo(xw.z), bf_hi(xw.z), bf_lo(xw.w), bf_hi(xw.w)};
;                     *(u32x4*)(xb + off) = pack8(v0, v1);
;                     sq += (v0[0] * v0[0] + v0[1] * v0[1]) + (v0[2] * v0[2] + v0[3] * v0[3]) + (v1[0] * v1[0] + v1[1] * v1[1]) + (v1[2] * v1[2] + v1[3] * v1[3]);
;                 }
	v_lshlrev_b32_e32 v246, 16, v198
	v_and_b32_e32 v247, 0xffff0000, v198
	v_lshlrev_b32_e32 v248, 16, v199
	v_and_b32_e32 v249, 0xffff0000, v199
	v_pk_add_f32 v[78:79], v[78:79], v[246:247]
	v_pk_add_f32 v[80:81], v[80:81], v[248:249]
	v_lshlrev_b32_e32 v246, 16, v200
	v_and_b32_e32 v247, 0xffff0000, v200
	v_lshlrev_b32_e32 v248, 16, v201
	v_and_b32_e32 v249, 0xffff0000, v201
	v_pk_add_f32 v[74:75], v[74:75], v[246:247]
	v_pk_add_f32 v[76:77], v[76:77], v[248:249]
	v_cvt_pk_bf16_f32 v198, v78, v79
	v_cvt_pk_bf16_f32 v199, v80, v81
	v_cvt_pk_bf16_f32 v200, v74, v75
	v_cvt_pk_bf16_f32 v201, v76, v77
	global_store_dwordx4 v153, v[198:201], s[30:31]
	v_pk_mul_f32 v[250:251], v[78:79], v[78:79]
	v_pk_fma_f32 v[250:251], v[80:81], v[80:81], v[250:251]
	v_pk_fma_f32 v[250:251], v[74:75], v[74:75], v[250:251]
	v_pk_fma_f32 v[250:251], v[76:77], v[76:77], v[250:251]
	s_waitcnt vmcnt(15)
	v_lshlrev_b32_e32 v246, 16, v202
	v_and_b32_e32 v247, 0xffff0000, v202
	v_lshlrev_b32_e32 v248, 16, v203
	v_and_b32_e32 v249, 0xffff0000, v203
	v_pk_add_f32 v[70:71], v[70:71], v[246:247]
	v_pk_add_f32 v[72:73], v[72:73], v[248:249]
	v_lshlrev_b32_e32 v246, 16, v204
	v_and_b32_e32 v247, 0xffff0000, v204
	v_lshlrev_b32_e32 v248, 16, v205
	v_and_b32_e32 v249, 0xffff0000, v205
	v_pk_add_f32 v[66:67], v[66:67], v[246:247]
	v_pk_add_f32 v[68:69], v[68:69], v[248:249]
	v_cvt_pk_bf16_f32 v202, v70, v71
	v_cvt_pk_bf16_f32 v203, v72, v73
	v_cvt_pk_bf16_f32 v204, v66, v67
	v_cvt_pk_bf16_f32 v205, v68, v69
	global_store_dwordx4 v153, v[202:205], s[30:31] offset:64
	v_pk_fma_f32 v[250:251], v[70:71], v[70:71], v[250:251]
	v_pk_fma_f32 v[250:251], v[72:73], v[72:73], v[250:251]
	v_pk_fma_f32 v[250:251], v[66:67], v[66:67], v[250:251]
	v_pk_fma_f32 v[250:251], v[68:69], v[68:69], v[250:251]
	v_add_f32_e32 v143, v250, v251
	s_waitcnt vmcnt(15)
	v_lshlrev_b32_e32 v246, 16, v206
	v_and_b32_e32 v247, 0xffff0000, v206
	v_lshlrev_b32_e32 v248, 16, v207
	v_and_b32_e32 v249, 0xffff0000, v207
	v_pk_add_f32 v[62:63], v[62:63], v[246:247]
	v_pk_add_f32 v[64:65], v[64:65], v[248:249]
	v_lshlrev_b32_e32 v246, 16, v208
	v_and_b32_e32 v247, 0xffff0000, v208
	v_lshlrev_b32_e32 v248, 16, v209
	v_and_b32_e32 v249, 0xffff0000, v209
	v_pk_add_f32 v[58:59], v[58:59], v[246:247]
	v_pk_add_f32 v[60:61], v[60:61], v[248:249]
	v_cvt_pk_bf16_f32 v206, v62, v63
	v_cvt_pk_bf16_f32 v207, v64, v65
	v_cvt_pk_bf16_f32 v208, v58, v59
	v_cvt_pk_bf16_f32 v209, v60, v61
	global_store_dwordx4 v154, v[206:209], s[30:31]
	v_pk_mul_f32 v[250:251], v[62:63], v[62:63]
	v_pk_fma_f32 v[250:251], v[64:65], v[64:65], v[250:251]
	v_pk_fma_f32 v[250:251], v[58:59], v[58:59], v[250:251]
	v_pk_fma_f32 v[250:251], v[60:61], v[60:61], v[250:251]
	s_waitcnt vmcnt(15)
	v_lshlrev_b32_e32 v246, 16, v210
	v_and_b32_e32 v247, 0xffff0000, v210
	v_lshlrev_b32_e32 v248, 16, v211
	v_and_b32_e32 v249, 0xffff0000, v211
	v_pk_add_f32 v[54:55], v[54:55], v[246:247]
	v_pk_add_f32 v[56:57], v[56:57], v[248:249]
	v_lshlrev_b32_e32 v246, 16, v212
	v_and_b32_e32 v247, 0xffff0000, v212
	v_lshlrev_b32_e32 v248, 16, v213
	v_and_b32_e32 v249, 0xffff0000, v213
	v_pk_add_f32 v[50:51], v[50:51], v[246:247]
	v_pk_add_f32 v[52:53], v[52:53], v[248:249]
	v_cvt_pk_bf16_f32 v210, v54, v55
	v_cvt_pk_bf16_f32 v211, v56, v57
	v_cvt_pk_bf16_f32 v212, v50, v51
	v_cvt_pk_bf16_f32 v213, v52, v53
	global_store_dwordx4 v154, v[210:213], s[30:31] offset:64
	v_pk_fma_f32 v[250:251], v[54:55], v[54:55], v[250:251]
	v_pk_fma_f32 v[250:251], v[56:57], v[56:57], v[250:251]
	v_pk_fma_f32 v[250:251], v[50:51], v[50:51], v[250:251]
	v_pk_fma_f32 v[250:251], v[52:53], v[52:53], v[250:251]
	v_add_f32_e32 v144, v250, v251
	s_waitcnt vmcnt(15)
	v_lshlrev_b32_e32 v246, 16, v214
	v_and_b32_e32 v247, 0xffff0000, v214
	v_lshlrev_b32_e32 v248, 16, v215
	v_and_b32_e32 v249, 0xffff0000, v215
	v_pk_add_f32 v[46:47], v[46:47], v[246:247]
	v_pk_add_f32 v[48:49], v[48:49], v[248:249]
	v_lshlrev_b32_e32 v246, 16, v216
	v_and_b32_e32 v247, 0xffff0000, v216
	v_lshlrev_b32_e32 v248, 16, v217
	v_and_b32_e32 v249, 0xffff0000, v217
	v_pk_add_f32 v[42:43], v[42:43], v[246:247]
	v_pk_add_f32 v[44:45], v[44:45], v[248:249]
	v_cvt_pk_bf16_f32 v214, v46, v47
	v_cvt_pk_bf16_f32 v215, v48, v49
	v_cvt_pk_bf16_f32 v216, v42, v43
	v_cvt_pk_bf16_f32 v217, v44, v45
	global_store_dwordx4 v155, v[214:217], s[30:31]
	v_pk_mul_f32 v[250:251], v[46:47], v[46:47]
	v_pk_fma_f32 v[250:251], v[48:49], v[48:49], v[250:251]
	v_pk_fma_f32 v[250:251], v[42:43], v[42:43], v[250:251]
	v_pk_fma_f32 v[250:251], v[44:45], v[44:45], v[250:251]
	s_waitcnt vmcnt(15)
	v_lshlrev_b32_e32 v246, 16, v218
	v_and_b32_e32 v247, 0xffff0000, v218
	v_lshlrev_b32_e32 v248, 16, v219
	v_and_b32_e32 v249, 0xffff0000, v219
	v_pk_add_f32 v[38:39], v[38:39], v[246:247]
	v_pk_add_f32 v[40:41], v[40:41], v[248:249]
	v_lshlrev_b32_e32 v246, 16, v220
	v_and_b32_e32 v247, 0xffff0000, v220
	v_lshlrev_b32_e32 v248, 16, v221
	v_and_b32_e32 v249, 0xffff0000, v221
	v_pk_add_f32 v[34:35], v[34:35], v[246:247]
	v_pk_add_f32 v[36:37], v[36:37], v[248:249]
	v_cvt_pk_bf16_f32 v218, v38, v39
	v_cvt_pk_bf16_f32 v219, v40, v41
	v_cvt_pk_bf16_f32 v220, v34, v35
	v_cvt_pk_bf16_f32 v221, v36, v37
	global_store_dwordx4 v155, v[218:221], s[30:31] offset:64
	v_pk_fma_f32 v[250:251], v[38:39], v[38:39], v[250:251]
	v_pk_fma_f32 v[250:251], v[40:41], v[40:41], v[250:251]
	v_pk_fma_f32 v[250:251], v[34:35], v[34:35], v[250:251]
	v_pk_fma_f32 v[250:251], v[36:37], v[36:37], v[250:251]
	v_add_f32_e32 v145, v250, v251
	s_waitcnt vmcnt(15)
; __device__ __forceinline__ float bf_lo(unsigned w) { return __uint_as_float(w << 16); }
; __device__ __forceinline__ float bf_hi(unsigned w) { return __uint_as_float(w & 0xffff0000u); }
; __device__ __forceinline__ u32x4 pack8(f32x4 a, f32x4 b) { u32x4 w; w.x = cvt_pk_bf16(a[0], a[1]); w.y = cvt_pk_bf16(a[2], a[3]); w.z = cvt_pk_bf16(b[0], b[1]); w.w = cvt_pk_bf16(b[2], b[3]); return w; }
;     __device__ __forceinline__ void operator()(f32x4 (&acc)[2][2][4][2], const Unit& u, int wr, int wc, int fr, int fq) const {
;     ...
;                 for (int bj = 0; bj < 2; ++bj) {
;                     const size_t off = (size_t)row * D + col0 + bj * 32;
;                     const u32x4 xw = *(const u32x4*)(xin + off);
;                     const f32x4 v0 = acc[ai][bj][m][0] + (f32x4){bf_lo(xw.x), bf_hi(xw.x), bf_lo(xw.y), bf_hi(xw.y)}, v1 = acc[ai][bj][m][1] + (f32x4){bf_lo(xw.z), bf_hi(xw.z), bf_lo(xw.w), bf_hi(xw.w)};
;                     *(u32x4*)(xb + off) = pack8(v0, v1);
;                     sq += (v0[0] * v0[0] + v0[1] * v0[1]) + (v0[2] * v0[2] + v0[3] * v0[3]) + (v1[0] * v1[0] + v1[1] * v1[1]) + (v1[2] * v1[2] + v1[3] * v1[3]);
;                 }
;                 sq += __shfl_xor(sq, 16); sq += __shfl_xor(sq, 32);
;                 if (fq == 0) ss[(size_t)row * 32 + u.pn * 4 + wc] = sq;
	v_lshlrev_b32_e32 v246, 16, v222
	v_and_b32_e32 v247, 0xffff0000, v222
	v_lshlrev_b32_e32 v248, 16, v223
	v_and_b32_e32 v249, 0xffff0000, v223
	v_pk_add_f32 v[30:31], v[30:31], v[246:247]
	v_pk_add_f32 v[32:33], v[32:33], v[248:249]
	v_lshlrev_b32_e32 v246, 16, v224
	v_and_b32_e32 v247, 0xffff0000, v224
	v_lshlrev_b32_e32 v248, 16, v225
	v_and_b32_e32 v249, 0xffff0000, v225
	v_pk_add_f32 v[26:27], v[26:27], v[246:247]
	v_pk_add_f32 v[28:29], v[28:29], v[248:249]
	v_cvt_pk_bf16_f32 v222, v30, v31
	v_cvt_pk_bf16_f32 v223, v32, v33
	v_cvt_pk_bf16_f32 v224, v26, v27
	v_cvt_pk_bf16_f32 v225, v28, v29
	global_store_dwordx4 v156, v[222:225], s[30:31]
	v_pk_mul_f32 v[250:251], v[30:31], v[30:31]
	v_pk_fma_f32 v[250:251], v[32:33], v[32:33], v[250:251]
	v_pk_fma_f32 v[250:251], v[26:27], v[26:27], v[250:251]
	v_pk_fma_f32 v[250:251], v[28:29], v[28:29], v[250:251]
	s_waitcnt vmcnt(15)
	v_lshlrev_b32_e32 v246, 16, v226
	v_and_b32_e32 v247, 0xffff0000, v226
	v_lshlrev_b32_e32 v248, 16, v227
	v_and_b32_e32 v249, 0xffff0000, v227
	v_pk_add_f32 v[22:23], v[22:23], v[246:247]
	v_pk_add_f32 v[24:25], v[24:25], v[248:249]
	v_lshlrev_b32_e32 v246, 16, v228
	v_and_b32_e32 v247, 0xffff0000, v228
	v_lshlrev_b32_e32 v248, 16, v229
	v_and_b32_e32 v249, 0xffff0000, v229
	v_pk_add_f32 v[18:19], v[18:19], v[246:247]
	v_pk_add_f32 v[20:21], v[20:21], v[248:249]
	v_cvt_pk_bf16_f32 v226, v22, v23
	v_cvt_pk_bf16_f32 v227, v24, v25
	v_cvt_pk_bf16_f32 v228, v18, v19
	v_cvt_pk_bf16_f32 v229, v20, v21
	global_store_dwordx4 v156, v[226:229], s[30:31] offset:64
	v_pk_fma_f32 v[250:251], v[22:23], v[22:23], v[250:251]
	v_pk_fma_f32 v[250:251], v[24:25], v[24:25], v[250:251]
	v_pk_fma_f32 v[250:251], v[18:19], v[18:19], v[250:251]
	v_pk_fma_f32 v[250:251], v[20:21], v[20:21], v[250:251]
	v_add_f32_e32 v162, v250, v251
	s_waitcnt vmcnt(15)
	v_lshlrev_b32_e32 v246, 16, v230
	v_and_b32_e32 v247, 0xffff0000, v230
	v_lshlrev_b32_e32 v248, 16, v231
	v_and_b32_e32 v249, 0xffff0000, v231
	v_pk_add_f32 v[14:15], v[14:15], v[246:247]
	v_pk_add_f32 v[16:17], v[16:17], v[248:249]
	v_lshlrev_b32_e32 v246, 16, v232
	v_and_b32_e32 v247, 0xffff0000, v232
	v_lshlrev_b32_e32 v248, 16, v233
	v_and_b32_e32 v249, 0xffff0000, v233
	v_pk_add_f32 v[10:11], v[10:11], v[246:247]
	v_pk_add_f32 v[12:13], v[12:13], v[248:249]
	v_cvt_pk_bf16_f32 v230, v14, v15
	v_cvt_pk_bf16_f32 v231, v16, v17
	v_cvt_pk_bf16_f32 v232, v10, v11
	v_cvt_pk_bf16_f32 v233, v12, v13
	global_store_dwordx4 v157, v[230:233], s[30:31]
	v_pk_mul_f32 v[250:251], v[14:15], v[14:15]
	v_pk_fma_f32 v[250:251], v[16:17], v[16:17], v[250:251]
	v_pk_fma_f32 v[250:251], v[10:11], v[10:11], v[250:251]
	v_pk_fma_f32 v[250:251], v[12:13], v[12:13], v[250:251]
	s_waitcnt vmcnt(15)
	v_lshlrev_b32_e32 v246, 16, v234
	v_and_b32_e32 v247, 0xffff0000, v234
	v_lshlrev_b32_e32 v248, 16, v235
	v_and_b32_e32 v249, 0xffff0000, v235
	v_pk_add_f32 v[6:7], v[6:7], v[246:247]
	v_pk_add_f32 v[8:9], v[8:9], v[248:249]
	v_lshlrev_b32_e32 v246, 16, v236
	v_and_b32_e32 v247, 0xffff0000, v236
	v_lshlrev_b32_e32 v248, 16, v237
	v_and_b32_e32 v249, 0xffff0000, v237
	v_pk_add_f32 v[2:3], v[2:3], v[246:247]
	v_pk_add_f32 v[4:5], v[4:5], v[248:249]
	v_cvt_pk_bf16_f32 v234, v6, v7
	v_cvt_pk_bf16_f32 v235, v8, v9
	v_cvt_pk_bf16_f32 v236, v2, v3
	v_cvt_pk_bf16_f32 v237, v4, v5
	global_store_dwordx4 v157, v[234:237], s[30:31] offset:64
	v_pk_fma_f32 v[250:251], v[6:7], v[6:7], v[250:251]
	v_pk_fma_f32 v[250:251], v[8:9], v[8:9], v[250:251]
	v_pk_fma_f32 v[250:251], v[2:3], v[2:3], v[250:251]
	v_pk_fma_f32 v[250:251], v[4:5], v[4:5], v[250:251]
	v_add_f32_e32 v238, v250, v251
	ds_bpermute_b32 v174, v239, v140
	ds_bpermute_b32 v175, v239, v141
	ds_bpermute_b32 v176, v239, v142
	ds_bpermute_b32 v177, v239, v143
	ds_bpermute_b32 v178, v239, v144
	ds_bpermute_b32 v179, v239, v145
	ds_bpermute_b32 v180, v239, v162
	ds_bpermute_b32 v181, v239, v238
	s_waitcnt lgkmcnt(0)
	v_add_f32_e32 v140, v140, v174
	v_add_f32_e32 v141, v141, v175
	v_add_f32_e32 v142, v142, v176
	v_add_f32_e32 v143, v143, v177
	v_add_f32_e32 v144, v144, v178
	v_add_f32_e32 v145, v145, v179
	v_add_f32_e32 v162, v162, v180
	v_add_f32_e32 v238, v238, v181
	ds_bpermute_b32 v174, v252, v140
	ds_bpermute_b32 v175, v252, v141
	ds_bpermute_b32 v176, v252, v142
	ds_bpermute_b32 v177, v252, v143
	ds_bpermute_b32 v178, v252, v144
	ds_bpermute_b32 v179, v252, v145
	ds_bpermute_b32 v180, v252, v162
	ds_bpermute_b32 v181, v252, v238
	s_waitcnt lgkmcnt(0)
	v_add_f32_e32 v140, v140, v174
	v_add_f32_e32 v141, v141, v175
	v_add_f32_e32 v142, v142, v176
	v_add_f32_e32 v143, v143, v177
	v_add_f32_e32 v144, v144, v178
	v_add_f32_e32 v145, v145, v179
	v_add_f32_e32 v162, v162, v180
	v_add_f32_e32 v238, v238, v181
	s_and_saveexec_b64 s[12:13], s[36:37]
	global_store_dword v158, v140, s[34:35]
	global_store_dword v158, v141, s[34:35] offset:2048
	global_store_dword v159, v142, s[34:35]
	global_store_dword v159, v143, s[34:35] offset:2048
	global_store_dword v160, v144, s[34:35]
	global_store_dword v160, v145, s[34:35] offset:2048
	global_store_dword v161, v162, s[34:35]
	global_store_dword v161, v238, s[34:35] offset:2048
	s_mov_b32 s65, 0x10000
	s_or_b64 exec, exec, s[12:13]
	s_and_b64 vcc, exec, s[38:39]
	s_mov_b64 s[12:13], -1
	s_cbranch_vccnz .LBB0_942
	s_andn2_b64 vcc, exec, s[18:19]
	s_cbranch_vccnz .LBB0_941
	s_barrier
	s_branch .LBB0_941
